# hyena FFT: forward S=1 pass, spectral multiply and inverse S=1 pass fused into one LDS round trip; passes with stride <= threads-per-transform use hoisted twiddles/addresses; filter transform stores i
# speedup vs baseline: 1.1432x; 1.0195x over previous
; DI float cos2pi(float x) { return __builtin_amdgcn_cosf(x); }
; DI float sin2pi(float x) { return __builtin_amdgcn_sinf(x); }
; template <bool INV>
; DI void fft_lds(float2* buf_, int L, int logL, int gtid, int NTG) {
;     ...
;     for (; s >= 2; s >>= 2) {
;       const int S = s >> 1;
;       const float i4 = 0.25f / (float)S;
; #pragma unroll 8
;       for (int t = gtid; t < (L >> 2); t += NTG) {
;         const int k = t & (S - 1), base = ((t - k) << 2) | k;
;         const v2f a0 = buf[base], a1 = buf[base + S], a2 = buf[base + 2 * S], a3 = buf[base + 3 * S];
;         const float fr = (float)k * i4;
;         const v2f w1 = v2f{cos2pi(fr), sin2pi(fr)};
;         const v2f w2 = vcmul(w1, w1);
;         const v2f x0 = a0 + a2;
;         const v2f x2 = vcmulc(a0 - a2, w1);
;         const v2f x1 = a1 + a3;
;         const v2f d13 = vcmulc(a1 - a3, w1);
;         const v2f x3 = v2f{d13.y, -d13.x};
;         buf[base] = x0 + x1;
;         buf[base + S] = vcmulc(x0 - x1, w2);
;         buf[base + 2 * S] = x2 + x3;
;         buf[base + 3 * S] = vcmulc(x2 - x3, w2);
;       }
; DI void hyena_item(const Ctx& c, int ch, float* red) {
;     ...
;       fft_lds<false>(buf0, L, logL, tid, NTHR);
;       for (int n = tid; n < L; n += NTHR) SPEC[p * 16384 + n] = buf0[n];
.LBB0_610:
	s_and_saveexec_b64 s[24:25], s[12:13]
	s_cbranch_execz .LBB0_609
	s_lshr_b32 s9, s6, 1
	s_cmp_eq_u32 s88, 0x200
	s_cbranch_scc1 .Lffs_pg1
	s_cmp_gt_u32 s9, 256
	s_cbranch_scc1 .Lffs_pg8_skip
	s_cmp_eq_u32 s9, 256
	s_cbranch_scc1 .Lffs_pg8_256
	s_cmp_eq_u32 s9, 64
	s_cbranch_scc1 .Lffs_pg8_64
	s_cmp_eq_u32 s9, 16
	s_cbranch_scc1 .Lffs_pg8_16
	s_cmp_eq_u32 s9, 4
	s_cbranch_scc1 .Lffs_pg8_4
	v_mov_b32_e32 v24, 0x50
	v_lshlrev_b32_e32 v254, 2, v34
	v_bfe_u32 v246, v254, 5, 2
	v_bfe_u32 v247, v254, 6, 1
	v_lshl_or_b32 v246, v246, 2, v246
	v_lshl_or_b32 v246, v247, 4, v246
	v_xor_b32_e32 v246, v246, v254
	v_lshlrev_b32_e32 v246, 3, v246
	v_add_u32_e32 v12, v24, v246
	v_xad_u32 v13, v246, 8, v24
	v_xad_u32 v14, v246, 16, v24
	v_xad_u32 v15, v246, 24, v24
	v_mul_u32_u24_e32 v20, 24, v34
	v_mov_b32_e32 v21, 0
	v_lshl_add_u64 v[20:21], v[20:21], 0, v[52:53]
	s_mov_b32 s0, 0x4000
	s_mov_b32 s1, 0
	v_lshl_add_u64 v[22:23], v[20:21], 0, s[0:1]
	s_mov_b32 s0, 0x8000
	s_mov_b32 s5, 4
.Lffg_pg8:
	ds_read_b64 v[4:5], v12
	ds_read_b64 v[6:7], v13
	ds_read_b64 v[8:9], v14
	ds_read_b64 v[10:11], v15
	ds_read_b64 v[230:231], v12 offset:16384
	ds_read_b64 v[232:233], v13 offset:16384
	ds_read_b64 v[234:235], v14 offset:16384
	ds_read_b64 v[236:237], v15 offset:16384
	s_waitcnt lgkmcnt(4)
	v_add_f32_e32 v25, v4, v8
	v_sub_f32_e32 v0, v4, v8
	v_add_f32_e32 v3, v6, v10
	v_sub_f32_e32 v251, v6, v10
	v_add_f32_e32 v26, v5, v9
	v_sub_f32_e32 v2, v5, v9
	v_add_f32_e32 v250, v7, v11
	v_sub_f32_e32 v252, v7, v11
	v_add_f32_e32 v4, v25, v3
	v_add_f32_e32 v5, v26, v250
	v_sub_f32_e32 v6, v25, v3
	v_sub_f32_e32 v7, v26, v250
	v_add_f32_e32 v8, v0, v252
	v_sub_f32_e32 v9, v2, v251
	v_sub_f32_e32 v10, v0, v252
	v_add_f32_e32 v11, v2, v251
	global_store_dwordx4 v[20:21], v[4:7], off
	global_store_dwordx4 v[20:21], v[8:11], off offset:16
	s_waitcnt lgkmcnt(0)
	v_add_f32_e32 v25, v230, v234
	v_sub_f32_e32 v0, v230, v234
	v_add_f32_e32 v3, v232, v236
	v_sub_f32_e32 v251, v232, v236
	v_add_f32_e32 v26, v231, v235
	v_sub_f32_e32 v2, v231, v235
	v_add_f32_e32 v250, v233, v237
	v_sub_f32_e32 v252, v233, v237
	v_add_f32_e32 v230, v25, v3
	v_add_f32_e32 v231, v26, v250
	v_sub_f32_e32 v232, v25, v3
	v_sub_f32_e32 v233, v26, v250
	v_add_f32_e32 v234, v0, v252
	v_sub_f32_e32 v235, v2, v251
	v_sub_f32_e32 v236, v0, v252
	v_add_f32_e32 v237, v2, v251
	global_store_dwordx4 v[22:23], v[230:233], off
	global_store_dwordx4 v[22:23], v[234:237], off offset:16
	v_add_u32_e32 v12, 0x8000, v12
	v_add_u32_e32 v13, 0x8000, v13
	v_add_u32_e32 v14, 0x8000, v14
	v_add_u32_e32 v15, 0x8000, v15
	v_lshl_add_u64 v[20:21], v[20:21], 0, s[0:1]
	v_lshl_add_u64 v[22:23], v[22:23], 0, s[0:1]
	s_add_i32 s5, s5, -1
	s_cmp_lg_u32 s5, 0
	s_cbranch_scc1 .Lffg_pg8
	s_branch .LBB0_609
.Lffs_pg8_4:
	v_mov_b32_e32 v24, 0x50
	s_movk_i32 s0, 0x20
	s_movk_i32 s1, 0x40
	s_movk_i32 s4, 0x60
	v_and_b32_e32 v254, 3, v34
	v_sub_u32_e32 v246, v34, v254
	v_lshl_or_b32 v246, v246, 2, v254
	v_cvt_f32_u32_e32 v254, v254
	v_mul_f32_e32 v254, 0x3d800000, v254
	v_cos_f32_e32 v20, v254
	v_sin_f32_e32 v21, v254
	v_bfe_u32 v247, v246, 5, 2
	v_bfe_u32 v248, v246, 6, 1
	v_lshl_or_b32 v247, v247, 2, v247
	v_lshl_or_b32 v247, v248, 4, v247
	v_xor_b32_e32 v247, v247, v246
	v_lshlrev_b32_e32 v247, 3, v247
	v_add_u32_e32 v12, v24, v247
	v_xad_u32 v13, v247, s0, v24
	v_xad_u32 v14, v247, s1, v24
	v_xad_u32 v15, v247, s4, v24
	v_mul_f32_e32 v22, v21, v21
	v_mul_f32_e32 v23, v21, v20
	v_fma_f32 v22, v20, v20, -v22
	v_fma_f32 v23, v20, v21, v23
	ds_read_b64 v[4:5], v12
	ds_read_b64 v[6:7], v13
	ds_read_b64 v[8:9], v14
	ds_read_b64 v[10:11], v15
	s_mov_b32 s5, 4
	s_waitcnt lgkmcnt(0)
.Lffl_pg8_4:
	ds_read_b64 v[230:231], v12 offset:16384
	ds_read_b64 v[232:233], v13 offset:16384
	ds_read_b64 v[234:235], v14 offset:16384
	ds_read_b64 v[236:237], v15 offset:16384
	s_waitcnt lgkmcnt(8)
	v_add_f32_e32 v25, v4, v8
	v_sub_f32_e32 v0, v4, v8
	v_add_f32_e32 v3, v6, v10
	v_sub_f32_e32 v251, v6, v10
	v_add_f32_e32 v26, v5, v9
	v_sub_f32_e32 v2, v5, v9
	v_add_f32_e32 v250, v7, v11
	v_sub_f32_e32 v252, v7, v11
	v_mul_f32_e32 v246, v0, v20
	v_mul_f32_e32 v247, v0, v21
	v_fma_f32 v253, v2, v21, v246
	v_fma_f32 v254, v2, v20, -v247
	v_mul_f32_e32 v246, v251, v20
	v_mul_f32_e32 v247, v251, v21
	v_fma_f32 v248, v252, v21, v246
	v_fma_f32 v249, v252, v20, -v247
	v_add_f32_e32 v4, v25, v3
	v_add_f32_e32 v5, v26, v250
	v_sub_f32_e32 v25, v25, v3
	v_sub_f32_e32 v26, v26, v250
	v_mul_f32_e32 v246, v25, v22
	v_mul_f32_e32 v247, v25, v23
	v_fma_f32 v6, v26, v23, v246
	v_fma_f32 v7, v26, v22, -v247
	v_add_f32_e32 v8, v253, v249
	v_sub_f32_e32 v9, v254, v248
	v_sub_f32_e32 v3, v253, v249
	v_add_f32_e32 v250, v254, v248
	v_mul_f32_e32 v246, v3, v22
	v_mul_f32_e32 v247, v3, v23
	v_fma_f32 v10, v250, v23, v246
	v_fma_f32 v11, v250, v22, -v247
	ds_write_b64 v12, v[4:5]
	ds_write_b64 v13, v[6:7]
	ds_write_b64 v14, v[8:9]
	ds_write_b64 v15, v[10:11]
	ds_read_b64 v[4:5], v12 offset:32768
	ds_read_b64 v[6:7], v13 offset:32768
	ds_read_b64 v[8:9], v14 offset:32768
	ds_read_b64 v[10:11], v15 offset:32768
	s_waitcnt lgkmcnt(8)
	v_add_f32_e32 v25, v230, v234
	v_sub_f32_e32 v0, v230, v234
	v_add_f32_e32 v3, v232, v236
	v_sub_f32_e32 v251, v232, v236
	v_add_f32_e32 v26, v231, v235
	v_sub_f32_e32 v2, v231, v235
	v_add_f32_e32 v250, v233, v237
	v_sub_f32_e32 v252, v233, v237
	v_mul_f32_e32 v246, v0, v20
	v_mul_f32_e32 v247, v0, v21
	v_fma_f32 v253, v2, v21, v246
	v_fma_f32 v254, v2, v20, -v247
	v_mul_f32_e32 v246, v251, v20
	v_mul_f32_e32 v247, v251, v21
	v_fma_f32 v248, v252, v21, v246
	v_fma_f32 v249, v252, v20, -v247
	v_add_f32_e32 v230, v25, v3
	v_add_f32_e32 v231, v26, v250
	v_sub_f32_e32 v25, v25, v3
	v_sub_f32_e32 v26, v26, v250
	v_mul_f32_e32 v246, v25, v22
	v_mul_f32_e32 v247, v25, v23
	v_fma_f32 v232, v26, v23, v246
	v_fma_f32 v233, v26, v22, -v247
	v_add_f32_e32 v234, v253, v249
	v_sub_f32_e32 v235, v254, v248
	v_sub_f32_e32 v3, v253, v249
	v_add_f32_e32 v250, v254, v248
	v_mul_f32_e32 v246, v3, v22
	v_mul_f32_e32 v247, v3, v23
	v_fma_f32 v236, v250, v23, v246
	v_fma_f32 v237, v250, v22, -v247
	ds_write_b64 v12, v[230:231] offset:16384
	ds_write_b64 v13, v[232:233] offset:16384
	ds_write_b64 v14, v[234:235] offset:16384
	ds_write_b64 v15, v[236:237] offset:16384
	v_add_u32_e32 v12, 0x8000, v12
	v_add_u32_e32 v13, 0x8000, v13
	v_add_u32_e32 v14, 0x8000, v14
	v_add_u32_e32 v15, 0x8000, v15
	s_add_i32 s5, s5, -1
	s_cmp_lg_u32 s5, 0
	s_cbranch_scc1 .Lffl_pg8_4
	s_branch .LBB0_609
; DI float cos2pi(float x) { return __builtin_amdgcn_cosf(x); }
; DI float sin2pi(float x) { return __builtin_amdgcn_sinf(x); }
; template <bool INV>
; DI void fft_lds(float2* buf_, int L, int logL, int gtid, int NTG) {
;     ...
;     for (; s >= 2; s >>= 2) {
;       const int S = s >> 1;
;       const float i4 = 0.25f / (float)S;
; #pragma unroll 8
;       for (int t = gtid; t < (L >> 2); t += NTG) {
;         const int k = t & (S - 1), base = ((t - k) << 2) | k;
;         const v2f a0 = buf[base], a1 = buf[base + S], a2 = buf[base + 2 * S], a3 = buf[base + 3 * S];
;         const float fr = (float)k * i4;
;         const v2f w1 = v2f{cos2pi(fr), sin2pi(fr)};
;         const v2f w2 = vcmul(w1, w1);
;         const v2f x0 = a0 + a2;
;         const v2f x2 = vcmulc(a0 - a2, w1);
;         const v2f x1 = a1 + a3;
;         const v2f d13 = vcmulc(a1 - a3, w1);
;         const v2f x3 = v2f{d13.y, -d13.x};
;         buf[base] = x0 + x1;
;         buf[base + S] = vcmulc(x0 - x1, w2);
;         buf[base + 2 * S] = x2 + x3;
;         buf[base + 3 * S] = vcmulc(x2 - x3, w2);
;       }
.Lffs_pg8_16:
	v_mov_b32_e32 v24, 0x50
	s_movk_i32 s0, 0x80
	s_movk_i32 s1, 0x128
	s_movk_i32 s4, 0x1a8
	v_and_b32_e32 v254, 15, v34
	v_sub_u32_e32 v246, v34, v254
	v_lshl_or_b32 v246, v246, 2, v254
	v_cvt_f32_u32_e32 v254, v254
	v_mul_f32_e32 v254, 0x3c800000, v254
	v_cos_f32_e32 v20, v254
	v_sin_f32_e32 v21, v254
	v_lshl_add_u32 v12, v246, 3, v24
	v_add_u32_e32 v13, 0x80, v12
	v_add_u32_e32 v14, 0x100, v12
	v_add_u32_e32 v15, 0x180, v12
	v_bfe_u32 v247, v246, 5, 2
	v_bfe_u32 v248, v246, 6, 1
	v_lshl_or_b32 v247, v247, 2, v247
	v_lshl_or_b32 v247, v248, 4, v247
	v_xor_b32_e32 v247, v247, v246
	v_lshlrev_b32_e32 v247, 3, v247
	v_add_u32_e32 v16, v24, v247
	v_xad_u32 v17, v247, s0, v24
	v_xad_u32 v18, v247, s1, v24
	v_xad_u32 v19, v247, s4, v24
	v_mul_f32_e32 v22, v21, v21
	v_mul_f32_e32 v23, v21, v20
	v_fma_f32 v22, v20, v20, -v22
	v_fma_f32 v23, v20, v21, v23
	ds_read_b64 v[4:5], v12
	ds_read_b64 v[6:7], v13
	ds_read_b64 v[8:9], v14
	ds_read_b64 v[10:11], v15
	s_mov_b32 s5, 4
	s_waitcnt lgkmcnt(0)
.Lffl_pg8_16:
	ds_read_b64 v[230:231], v12 offset:16384
	ds_read_b64 v[232:233], v13 offset:16384
	ds_read_b64 v[234:235], v14 offset:16384
	ds_read_b64 v[236:237], v15 offset:16384
	s_waitcnt lgkmcnt(8)
	v_add_f32_e32 v25, v4, v8
	v_sub_f32_e32 v0, v4, v8
	v_add_f32_e32 v3, v6, v10
	v_sub_f32_e32 v251, v6, v10
	v_add_f32_e32 v26, v5, v9
	v_sub_f32_e32 v2, v5, v9
	v_add_f32_e32 v250, v7, v11
	v_sub_f32_e32 v252, v7, v11
	v_mul_f32_e32 v246, v0, v20
	v_mul_f32_e32 v247, v0, v21
	v_fma_f32 v253, v2, v21, v246
	v_fma_f32 v254, v2, v20, -v247
	v_mul_f32_e32 v246, v251, v20
	v_mul_f32_e32 v247, v251, v21
	v_fma_f32 v248, v252, v21, v246
	v_fma_f32 v249, v252, v20, -v247
	v_add_f32_e32 v4, v25, v3
	v_add_f32_e32 v5, v26, v250
	v_sub_f32_e32 v25, v25, v3
	v_sub_f32_e32 v26, v26, v250
	v_mul_f32_e32 v246, v25, v22
	v_mul_f32_e32 v247, v25, v23
	v_fma_f32 v6, v26, v23, v246
	v_fma_f32 v7, v26, v22, -v247
	v_add_f32_e32 v8, v253, v249
	v_sub_f32_e32 v9, v254, v248
	v_sub_f32_e32 v3, v253, v249
	v_add_f32_e32 v250, v254, v248
	v_mul_f32_e32 v246, v3, v22
	v_mul_f32_e32 v247, v3, v23
	v_fma_f32 v10, v250, v23, v246
	v_fma_f32 v11, v250, v22, -v247
	ds_write_b64 v16, v[4:5]
	ds_write_b64 v17, v[6:7]
	ds_write_b64 v18, v[8:9]
	ds_write_b64 v19, v[10:11]
	ds_read_b64 v[4:5], v12 offset:32768
	ds_read_b64 v[6:7], v13 offset:32768
	ds_read_b64 v[8:9], v14 offset:32768
	ds_read_b64 v[10:11], v15 offset:32768
	s_waitcnt lgkmcnt(8)
	v_add_f32_e32 v25, v230, v234
	v_sub_f32_e32 v0, v230, v234
	v_add_f32_e32 v3, v232, v236
	v_sub_f32_e32 v251, v232, v236
	v_add_f32_e32 v26, v231, v235
	v_sub_f32_e32 v2, v231, v235
	v_add_f32_e32 v250, v233, v237
	v_sub_f32_e32 v252, v233, v237
	v_mul_f32_e32 v246, v0, v20
	v_mul_f32_e32 v247, v0, v21
	v_fma_f32 v253, v2, v21, v246
	v_fma_f32 v254, v2, v20, -v247
	v_mul_f32_e32 v246, v251, v20
	v_mul_f32_e32 v247, v251, v21
	v_fma_f32 v248, v252, v21, v246
	v_fma_f32 v249, v252, v20, -v247
	v_add_f32_e32 v230, v25, v3
	v_add_f32_e32 v231, v26, v250
	v_sub_f32_e32 v25, v25, v3
	v_sub_f32_e32 v26, v26, v250
	v_mul_f32_e32 v246, v25, v22
	v_mul_f32_e32 v247, v25, v23
	v_fma_f32 v232, v26, v23, v246
	v_fma_f32 v233, v26, v22, -v247
	v_add_f32_e32 v234, v253, v249
	v_sub_f32_e32 v235, v254, v248
	v_sub_f32_e32 v3, v253, v249
	v_add_f32_e32 v250, v254, v248
	v_mul_f32_e32 v246, v3, v22
	v_mul_f32_e32 v247, v3, v23
	v_fma_f32 v236, v250, v23, v246
	v_fma_f32 v237, v250, v22, -v247
	ds_write_b64 v16, v[230:231] offset:16384
	ds_write_b64 v17, v[232:233] offset:16384
	ds_write_b64 v18, v[234:235] offset:16384
	ds_write_b64 v19, v[236:237] offset:16384
	v_add_u32_e32 v12, 0x8000, v12
	v_add_u32_e32 v13, 0x8000, v13
	v_add_u32_e32 v14, 0x8000, v14
	v_add_u32_e32 v15, 0x8000, v15
	v_add_u32_e32 v16, 0x8000, v16
	v_add_u32_e32 v17, 0x8000, v17
	v_add_u32_e32 v18, 0x8000, v18
	v_add_u32_e32 v19, 0x8000, v19
	s_add_i32 s5, s5, -1
	s_cmp_lg_u32 s5, 0
	s_cbranch_scc1 .Lffl_pg8_16
	s_branch .LBB0_609
.Lffs_pg8_64:
	v_mov_b32_e32 v24, 0x50
	v_and_b32_e32 v254, 63, v34
	v_sub_u32_e32 v246, v34, v254
	v_lshl_or_b32 v246, v246, 2, v254
	v_cvt_f32_u32_e32 v254, v254
	v_mul_f32_e32 v254, 0x3b800000, v254
	v_cos_f32_e32 v20, v254
	v_sin_f32_e32 v21, v254
	v_lshl_add_u32 v12, v246, 3, v24
	v_add_u32_e32 v13, 0x200, v12
	v_add_u32_e32 v14, 0x400, v12
	v_add_u32_e32 v15, 0x600, v12
	v_mul_f32_e32 v22, v21, v21
	v_mul_f32_e32 v23, v21, v20
	v_fma_f32 v22, v20, v20, -v22
	v_fma_f32 v23, v20, v21, v23
	ds_read_b64 v[4:5], v12
	ds_read_b64 v[6:7], v13
	ds_read_b64 v[8:9], v14
	ds_read_b64 v[10:11], v15
	s_mov_b32 s5, 4
	s_waitcnt lgkmcnt(0)

; DI float cos2pi(float x) { return __builtin_amdgcn_cosf(x); }
; DI float sin2pi(float x) { return __builtin_amdgcn_sinf(x); }
; template <bool INV>
; DI void fft_lds(float2* buf_, int L, int logL, int gtid, int NTG) {
;     ...
;     for (; s >= 2; s >>= 2) {
;       const int S = s >> 1;
;       const float i4 = 0.25f / (float)S;
; #pragma unroll 8
;       for (int t = gtid; t < (L >> 2); t += NTG) {
;         const int k = t & (S - 1), base = ((t - k) << 2) | k;
;         const v2f a0 = buf[base], a1 = buf[base + S], a2 = buf[base + 2 * S], a3 = buf[base + 3 * S];
;         const float fr = (float)k * i4;
;         const v2f w1 = v2f{cos2pi(fr), sin2pi(fr)};
;         const v2f w2 = vcmul(w1, w1);
;         const v2f x0 = a0 + a2;
;         const v2f x2 = vcmulc(a0 - a2, w1);
;         const v2f x1 = a1 + a3;
;         const v2f d13 = vcmulc(a1 - a3, w1);
;         const v2f x3 = v2f{d13.y, -d13.x};
;         buf[base] = x0 + x1;
;         buf[base + S] = vcmulc(x0 - x1, w2);
;         buf[base + 2 * S] = x2 + x3;
;         buf[base + 3 * S] = vcmulc(x2 - x3, w2);
;       }
.Lffs_pg8_256:
	v_mov_b32_e32 v24, 0x50
	v_and_b32_e32 v254, 255, v34
	v_sub_u32_e32 v246, v34, v254
	v_lshl_or_b32 v246, v246, 2, v254
	v_cvt_f32_u32_e32 v254, v254
	v_mul_f32_e32 v254, 0x3a800000, v254
	v_cos_f32_e32 v20, v254
	v_sin_f32_e32 v21, v254
	v_lshl_add_u32 v12, v246, 3, v24
	v_add_u32_e32 v13, 0x800, v12
	v_add_u32_e32 v14, 0x1000, v12
	v_add_u32_e32 v15, 0x1800, v12
	v_mul_f32_e32 v22, v21, v21
	v_mul_f32_e32 v23, v21, v20
	v_fma_f32 v22, v20, v20, -v22
	v_fma_f32 v23, v20, v21, v23
	ds_read_b64 v[4:5], v12
	ds_read_b64 v[6:7], v13
	ds_read_b64 v[8:9], v14
	ds_read_b64 v[10:11], v15
	s_mov_b32 s5, 4
	s_waitcnt lgkmcnt(0)

; DI float cos2pi(float x) { return __builtin_amdgcn_cosf(x); }
; DI float sin2pi(float x) { return __builtin_amdgcn_sinf(x); }
; template <bool INV>
; DI void fft_lds(float2* buf_, int L, int logL, int gtid, int NTG) {
;     ...
;     for (; s >= 2; s >>= 2) {
;       const int S = s >> 1;
;       const float i4 = 0.25f / (float)S;
; #pragma unroll 8
;       for (int t = gtid; t < (L >> 2); t += NTG) {
;         const int k = t & (S - 1), base = ((t - k) << 2) | k;
;         const v2f a0 = buf[base], a1 = buf[base + S], a2 = buf[base + 2 * S], a3 = buf[base + 3 * S];
;         const float fr = (float)k * i4;
;         const v2f w1 = v2f{cos2pi(fr), sin2pi(fr)};
;         const v2f w2 = vcmul(w1, w1);
;         const v2f x0 = a0 + a2;
;         const v2f x2 = vcmulc(a0 - a2, w1);
;         const v2f x1 = a1 + a3;
;         const v2f d13 = vcmulc(a1 - a3, w1);
;         const v2f x3 = v2f{d13.y, -d13.x};
;         buf[base] = x0 + x1;
;         buf[base + S] = vcmulc(x0 - x1, w2);
;         buf[base + 2 * S] = x2 + x3;
;         buf[base + 3 * S] = vcmulc(x2 - x3, w2);
;       }
; DI void hyena_item(const Ctx& c, int ch, float* red) {
;     ...
;       for (int n = tid; n < L; n += NTHR) SPEC[p * 16384 + n] = buf0[n];
.Lffs_pg8_skip:
	s_branch .Lffs_pg_skip
.Lffs_pg1:
	s_cmp_gt_u32 s9, 16
	s_cbranch_scc1 .Lffs_pg_skip
	s_cmp_eq_u32 s9, 16
	s_cbranch_scc1 .Lffs_pg1_16
	s_cmp_eq_u32 s9, 4
	s_cbranch_scc1 .Lffs_pg1_4
	v_mov_b32_e32 v24, 0x50
	v_lshlrev_b32_e32 v254, 2, v34
	v_bfe_u32 v246, v254, 5, 2
	v_bfe_u32 v247, v254, 6, 1
	v_lshl_or_b32 v246, v246, 2, v246
	v_lshl_or_b32 v246, v247, 4, v246
	v_xor_b32_e32 v246, v246, v254
	v_lshlrev_b32_e32 v246, 3, v246
	v_add_u32_e32 v12, v24, v246
	v_xad_u32 v13, v246, 8, v24
	v_xad_u32 v14, v246, 16, v24
	v_xad_u32 v15, v246, 24, v24
	v_mul_u32_u24_e32 v20, 24, v34
	v_mov_b32_e32 v21, 0
	v_lshl_add_u64 v[20:21], v[20:21], 0, v[52:53]
	ds_read_b64 v[4:5], v12
	ds_read_b64 v[6:7], v13
	ds_read_b64 v[8:9], v14
	ds_read_b64 v[10:11], v15
	s_waitcnt lgkmcnt(0)
	v_add_f32_e32 v25, v4, v8
	v_sub_f32_e32 v0, v4, v8
	v_add_f32_e32 v3, v6, v10
	v_sub_f32_e32 v251, v6, v10
	v_add_f32_e32 v26, v5, v9
	v_sub_f32_e32 v2, v5, v9
	v_add_f32_e32 v250, v7, v11
	v_sub_f32_e32 v252, v7, v11
	v_add_f32_e32 v4, v25, v3
	v_add_f32_e32 v5, v26, v250
	v_sub_f32_e32 v6, v25, v3
	v_sub_f32_e32 v7, v26, v250
	v_add_f32_e32 v8, v0, v252
	v_sub_f32_e32 v9, v2, v251
	v_sub_f32_e32 v10, v0, v252
	v_add_f32_e32 v11, v2, v251
	global_store_dwordx4 v[20:21], v[4:7], off
	global_store_dwordx4 v[20:21], v[8:11], off offset:16
	s_branch .LBB0_609

; DI void hyena_item(const Ctx& c, int ch, float* red) {
;     ...
;       fft_lds<false>(buf0, L, logL, tid, NTHR);
;       for (int n = tid; n < L; n += NTHR) SPEC[p * 16384 + n] = buf0[n];
;       __syncthreads();
.LBB0_618:
	s_and_saveexec_b64 s[0:1], s[42:43]
	s_mov_b64 s[6:7], 0x1000
	s_branch .LBB0_621
	s_mov_b64 s[4:5], 0
	v_mov_b64_e32 v[2:3], v[52:53]
	v_mov_b32_e32 v0, v92
	v_mov_b32_e32 v4, v34

; DI float cos2pi(float x) { return __builtin_amdgcn_cosf(x); }
; DI float sin2pi(float x) { return __builtin_amdgcn_sinf(x); }
; template <bool INV>
; DI void fft_lds(float2* buf_, int L, int logL, int gtid, int NTG) {
;     ...
;     for (; s >= 2; s >>= 2) {
;       const int S = s >> 1;
;       const float i4 = 0.25f / (float)S;
; #pragma unroll 8
;       for (int t = gtid; t < (L >> 2); t += NTG) {
;         const int k = t & (S - 1), base = ((t - k) << 2) | k;
;         const v2f a0 = buf[base], a1 = buf[base + S], a2 = buf[base + 2 * S], a3 = buf[base + 3 * S];
;         const float fr = (float)k * i4;
;         const v2f w1 = v2f{cos2pi(fr), sin2pi(fr)};
;         const v2f w2 = vcmul(w1, w1);
;         const v2f x0 = a0 + a2;
;         const v2f x2 = vcmulc(a0 - a2, w1);
;         const v2f x1 = a1 + a3;
;         const v2f d13 = vcmulc(a1 - a3, w1);
;         const v2f x3 = v2f{d13.y, -d13.x};
;         buf[base] = x0 + x1;
;         buf[base + S] = vcmulc(x0 - x1, w2);
;         buf[base + 2 * S] = x2 + x3;
;         buf[base + 3 * S] = vcmulc(x2 - x3, w2);
;       }
; DI void hyena_item(const Ctx& c, int ch, float* red) {
;     ...
;       fft_lds<false>(buf0, L, logL, tid, NTHR);
;       for (int n = tid; n < L; n += NTHR) SPEC[p * 16384 + n] = buf0[n];
.LBB0_650:
	s_and_saveexec_b64 s[24:25], s[12:13]
	s_cbranch_execz .LBB0_649
	s_lshr_b32 s9, s6, 1
	s_cmp_eq_u32 s88, 0x200
	s_cbranch_scc1 .Lffs_qg1
	s_cmp_gt_u32 s9, 256
	s_cbranch_scc1 .Lffs_qg8_skip
	s_cmp_eq_u32 s9, 256
	s_cbranch_scc1 .Lffs_qg8_256
	s_cmp_eq_u32 s9, 64
	s_cbranch_scc1 .Lffs_qg8_64
	s_cmp_eq_u32 s9, 16
	s_cbranch_scc1 .Lffs_qg8_16
	s_cmp_eq_u32 s9, 4
	s_cbranch_scc1 .Lffs_qg8_4
	v_mov_b32_e32 v24, 0x50
	v_lshlrev_b32_e32 v254, 2, v34
	v_bfe_u32 v246, v254, 5, 2
	v_bfe_u32 v247, v254, 6, 1
	v_lshl_or_b32 v246, v246, 2, v246
	v_lshl_or_b32 v246, v247, 4, v246
	v_xor_b32_e32 v246, v246, v254
	v_lshlrev_b32_e32 v246, 3, v246
	v_add_u32_e32 v12, v24, v246
	v_xad_u32 v13, v246, 8, v24
	v_xad_u32 v14, v246, 16, v24
	v_xad_u32 v15, v246, 24, v24
	v_mul_u32_u24_e32 v20, 24, v34
	v_mov_b32_e32 v21, 0
	v_lshl_add_u64 v[20:21], v[20:21], 0, v[54:55]
	s_mov_b32 s0, 0x4000
	s_mov_b32 s1, 0
	v_lshl_add_u64 v[22:23], v[20:21], 0, s[0:1]
	s_mov_b32 s0, 0x8000
	s_mov_b32 s5, 4

; DI float cos2pi(float x) { return __builtin_amdgcn_cosf(x); }
; DI float sin2pi(float x) { return __builtin_amdgcn_sinf(x); }
; template <bool INV>
; DI void fft_lds(float2* buf_, int L, int logL, int gtid, int NTG) {
;     ...
;     for (; s >= 2; s >>= 2) {
;       const int S = s >> 1;
;       const float i4 = 0.25f / (float)S;
; #pragma unroll 8
;       for (int t = gtid; t < (L >> 2); t += NTG) {
;         const int k = t & (S - 1), base = ((t - k) << 2) | k;
;         const v2f a0 = buf[base], a1 = buf[base + S], a2 = buf[base + 2 * S], a3 = buf[base + 3 * S];
;         const float fr = (float)k * i4;
;         const v2f w1 = v2f{cos2pi(fr), sin2pi(fr)};
;         const v2f w2 = vcmul(w1, w1);
;         const v2f x0 = a0 + a2;
;         const v2f x2 = vcmulc(a0 - a2, w1);
;         const v2f x1 = a1 + a3;
;         const v2f d13 = vcmulc(a1 - a3, w1);
;         const v2f x3 = v2f{d13.y, -d13.x};
;         buf[base] = x0 + x1;
;         buf[base + S] = vcmulc(x0 - x1, w2);
;         buf[base + 2 * S] = x2 + x3;
;         buf[base + 3 * S] = vcmulc(x2 - x3, w2);
;       }
; DI void hyena_item(const Ctx& c, int ch, float* red) {
;     ...
;       for (int n = tid; n < L; n += NTHR) SPEC[p * 16384 + n] = buf0[n];
.Lffs_qg1:
	s_cmp_gt_u32 s9, 16
	s_cbranch_scc1 .Lffs_qg_skip
	s_cmp_eq_u32 s9, 16
	s_cbranch_scc1 .Lffs_qg1_16
	s_cmp_eq_u32 s9, 4
	s_cbranch_scc1 .Lffs_qg1_4
	v_mov_b32_e32 v24, 0x50
	v_lshlrev_b32_e32 v254, 2, v34
	v_bfe_u32 v246, v254, 5, 2
	v_bfe_u32 v247, v254, 6, 1
	v_lshl_or_b32 v246, v246, 2, v246
	v_lshl_or_b32 v246, v247, 4, v246
	v_xor_b32_e32 v246, v246, v254
	v_lshlrev_b32_e32 v246, 3, v246
	v_add_u32_e32 v12, v24, v246
	v_xad_u32 v13, v246, 8, v24
	v_xad_u32 v14, v246, 16, v24
	v_xad_u32 v15, v246, 24, v24
	v_mul_u32_u24_e32 v20, 24, v34
	v_mov_b32_e32 v21, 0
	v_lshl_add_u64 v[20:21], v[20:21], 0, v[54:55]
	ds_read_b64 v[4:5], v12
	ds_read_b64 v[6:7], v13
	ds_read_b64 v[8:9], v14
	ds_read_b64 v[10:11], v15
	s_waitcnt lgkmcnt(0)
	v_add_f32_e32 v25, v4, v8
	v_sub_f32_e32 v0, v4, v8
	v_add_f32_e32 v3, v6, v10
	v_sub_f32_e32 v251, v6, v10
	v_add_f32_e32 v26, v5, v9
	v_sub_f32_e32 v2, v5, v9
	v_add_f32_e32 v250, v7, v11
	v_sub_f32_e32 v252, v7, v11
	v_add_f32_e32 v4, v25, v3
	v_add_f32_e32 v5, v26, v250
	v_sub_f32_e32 v6, v25, v3
	v_sub_f32_e32 v7, v26, v250
	v_add_f32_e32 v8, v0, v252
	v_sub_f32_e32 v9, v2, v251
	v_sub_f32_e32 v10, v0, v252
	v_add_f32_e32 v11, v2, v251
	global_store_dwordx4 v[20:21], v[4:7], off
	global_store_dwordx4 v[20:21], v[8:11], off offset:16
	s_branch .LBB0_649

; DI void hyena_item(const Ctx& c, int ch, float* red) {
;     ...
;       fft_lds<false>(buf0, L, logL, tid, NTHR);
;       for (int n = tid; n < L; n += NTHR) SPEC[p * 16384 + n] = buf0[n];
;       __syncthreads();
.LBB0_658:
	s_and_saveexec_b64 s[0:1], s[42:43]
	s_mov_b64 s[6:7], 0x1000
	s_branch .LBB0_661
	s_mov_b64 s[4:5], 0
	v_mov_b64_e32 v[2:3], v[54:55]
	v_mov_b32_e32 v0, v92
	v_mov_b32_e32 v4, v34

; DI float cos2pi(float x) { return __builtin_amdgcn_cosf(x); }
; DI float sin2pi(float x) { return __builtin_amdgcn_sinf(x); }
; DI float2 cmul(float2 a, float2 b) { return make_float2(a.x * b.x - a.y * b.y, a.x * b.y + a.y * b.x); }
; template <bool INV>
; DI void fft_lds(float2* buf_, int L, int logL, int gtid, int NTG) {
;     ...
;       for (int t = gtid; t < (L >> 2); t += NTG) {
;         const int k = t & (S - 1), base = ((t - k) << 2) | k;
;         const v2f a0 = buf[base], a1 = buf[base + S], a2 = buf[base + 2 * S], a3 = buf[base + 3 * S];
;         const float fr = (float)k * i4;
;         const v2f w1 = v2f{cos2pi(fr), sin2pi(fr)};
;         const v2f w2 = vcmul(w1, w1);
;         const v2f x0 = a0 + a2;
;         const v2f x2 = vcmulc(a0 - a2, w1);
;         const v2f x1 = a1 + a3;
;         const v2f d13 = vcmulc(a1 - a3, w1);
;         const v2f x3 = v2f{d13.y, -d13.x};
;         buf[base] = x0 + x1;
;         buf[base + S] = vcmulc(x0 - x1, w2);
;         buf[base + 2 * S] = x2 + x3;
;         buf[base + 3 * S] = vcmulc(x2 - x3, w2);
;       }
;     ...
;       for (int t = gtid; t < (L >> 2); t += NTG) {
;         const int k = t & (S - 1), base = ((t - k) << 2) | k;
;         const v2f p0 = buf[base], p1 = buf[base + S], p2 = buf[base + 2 * S], p3 = buf[base + 3 * S];
;         const float fr = (float)k * i4;
;         const v2f w1 = v2f{cos2pi(fr), sin2pi(fr)};
;         const v2f w2 = vcmul(w1, w1);
;         const v2f b1 = vcmul(p1, w2), b3 = vcmul(p3, w2);
;         const v2f q0 = p0 + b1, q1 = p0 - b1, q2 = p2 + b3, q3 = p2 - b3;
;         const v2f c2 = vcmul(q2, w1);
;         const v2f t3 = vcmul(q3, w1); const v2f c3 = v2f{-t3.y, t3.x};
;         buf[base] = q0 + c2;
;         buf[base + 2 * S] = q0 - c2;
;         buf[base + S] = q1 + c3;
;         buf[base + 3 * S] = q1 - c3;
;       }
; DI void hyena_item(const Ctx& c, int ch, float* red) {
;     ...
;         for (int n = gtid; n < L; n += NTG) bufg[n] = cmul(bufg[n], SPEC[p * 16384 + n]);
.LBB0_705:
	s_and_saveexec_b64 s[54:55], s[18:19]
	s_cbranch_execz .LBB0_704
	s_lshr_b32 s82, s6, 1
	s_cmp_eq_u32 s61, 64
	s_cbranch_scc1 .Lffs_f_n64
	s_cmp_gt_u32 s82, 256
	s_cbranch_scc1 .Lffs_fa_skip
	s_cmp_eq_u32 s82, 256
	s_cbranch_scc1 .Lffs_fa_256
	s_cmp_eq_u32 s82, 64
	s_cbranch_scc1 .Lffs_fa_64
	s_cmp_eq_u32 s82, 16
	s_cbranch_scc1 .Lffs_fa_16
	s_cmp_eq_u32 s82, 4
	s_cbranch_scc1 .Lffs_fa_4
	s_mov_b32 s0, 0x4000
	s_mov_b32 s1, 0
	v_lshlrev_b32_e32 v104, 2, v38
	v_add_u32_e32 v102, s24, v104
	v_ashrrev_i32_e32 v103, 31, v102
	v_lshl_add_u64 v[102:103], v[102:103], 3, s[2:3]
	v_bfe_u32 v105, v104, 5, 2
	v_bfe_u32 v106, v104, 6, 1
	v_lshl_or_b32 v105, v105, 2, v105
	v_lshl_or_b32 v105, v106, 4, v105
	v_xor_b32_e32 v105, v105, v104
	v_lshlrev_b32_e32 v105, 3, v105
	v_add_u32_e32 v72, v40, v105
	v_xad_u32 v73, v105, 8, v40
	v_xad_u32 v74, v105, 16, v40
	v_xad_u32 v75, v105, 24, v40
	s_mov_b32 s5, 4
.Lffu_fa_1:
	global_load_dwordx4 v[238:241], v[102:103], off
	global_load_dwordx4 v[242:245], v[102:103], off offset:16
	v_lshl_add_u64 v[102:103], v[102:103], 0, s[0:1]
	global_load_dwordx4 v[246:249], v[102:103], off
	global_load_dwordx4 v[250:253], v[102:103], off offset:16
	v_lshl_add_u64 v[102:103], v[102:103], 0, s[0:1]
	ds_read_b64 v[64:65], v72
	ds_read_b64 v[66:67], v73
	ds_read_b64 v[68:69], v74
	ds_read_b64 v[70:71], v75
	ds_read_b64 v[230:231], v72 offset:16384
	ds_read_b64 v[232:233], v73 offset:16384
	ds_read_b64 v[234:235], v74 offset:16384
	ds_read_b64 v[236:237], v75 offset:16384
	s_waitcnt lgkmcnt(4)
	v_add_f32_e32 v110, v64, v68
	v_sub_f32_e32 v112, v64, v68
	v_add_f32_e32 v30, v66, v70
	v_sub_f32_e32 v32, v66, v70
	v_add_f32_e32 v111, v65, v69
	v_sub_f32_e32 v113, v65, v69
	v_add_f32_e32 v31, v67, v71
	v_sub_f32_e32 v33, v67, v71
	v_add_f32_e32 v64, v110, v30
	v_add_f32_e32 v65, v111, v31
	v_sub_f32_e32 v66, v110, v30
	v_sub_f32_e32 v67, v111, v31
	v_add_f32_e32 v68, v112, v33
	v_sub_f32_e32 v69, v113, v32
	v_sub_f32_e32 v70, v112, v33
	v_add_f32_e32 v71, v113, v32
	s_waitcnt lgkmcnt(0)
	v_add_f32_e32 v110, v230, v234
	v_sub_f32_e32 v112, v230, v234
	v_add_f32_e32 v30, v232, v236
	v_sub_f32_e32 v32, v232, v236
	v_add_f32_e32 v111, v231, v235
	v_sub_f32_e32 v113, v231, v235
	v_add_f32_e32 v31, v233, v237
	v_sub_f32_e32 v33, v233, v237
	v_add_f32_e32 v230, v110, v30
	v_add_f32_e32 v231, v111, v31
	v_sub_f32_e32 v232, v110, v30
	v_sub_f32_e32 v233, v111, v31
	v_add_f32_e32 v234, v112, v33
	v_sub_f32_e32 v235, v113, v32
	v_sub_f32_e32 v236, v112, v33
	v_add_f32_e32 v237, v113, v32
	s_waitcnt vmcnt(2)
	v_mul_f32_e32 v47, v65, v239
	v_mul_f32_e32 v104, v65, v238
	v_fma_f32 v65, v64, v239, v104
	v_fma_f32 v64, v64, v238, -v47
	v_mul_f32_e32 v105, v67, v241
	v_mul_f32_e32 v106, v67, v240
	v_fma_f32 v67, v66, v241, v106
	v_fma_f32 v66, v66, v240, -v105
	v_mul_f32_e32 v47, v69, v243
	v_mul_f32_e32 v104, v69, v242
	v_fma_f32 v69, v68, v243, v104
	v_fma_f32 v68, v68, v242, -v47
	v_mul_f32_e32 v105, v71, v245
	v_mul_f32_e32 v106, v71, v244
	v_fma_f32 v71, v70, v245, v106
	v_fma_f32 v70, v70, v244, -v105
	v_add_f32_e32 v110, v64, v66
	v_sub_f32_e32 v112, v64, v66
	v_add_f32_e32 v30, v68, v70
	v_sub_f32_e32 v32, v68, v70
	v_add_f32_e32 v111, v65, v67
	v_sub_f32_e32 v113, v65, v67
	v_add_f32_e32 v31, v69, v71
	v_sub_f32_e32 v33, v69, v71
	v_add_f32_e32 v64, v110, v30
	v_add_f32_e32 v65, v111, v31
	v_sub_f32_e32 v66, v112, v33
	v_add_f32_e32 v67, v113, v32
	v_sub_f32_e32 v68, v110, v30
	v_sub_f32_e32 v69, v111, v31
	v_add_f32_e32 v70, v112, v33
	v_sub_f32_e32 v71, v113, v32
	ds_write_b64 v72, v[64:65]
	ds_write_b64 v73, v[66:67]
	ds_write_b64 v74, v[68:69]
	ds_write_b64 v75, v[70:71]
	s_waitcnt vmcnt(0)
	v_mul_f32_e32 v47, v231, v247
	v_mul_f32_e32 v104, v231, v246
	v_fma_f32 v231, v230, v247, v104
	v_fma_f32 v230, v230, v246, -v47
	v_mul_f32_e32 v105, v233, v249
	v_mul_f32_e32 v106, v233, v248
	v_fma_f32 v233, v232, v249, v106
	v_fma_f32 v232, v232, v248, -v105
	v_mul_f32_e32 v47, v235, v251
	v_mul_f32_e32 v104, v235, v250
	v_fma_f32 v235, v234, v251, v104
	v_fma_f32 v234, v234, v250, -v47
	v_mul_f32_e32 v105, v237, v253
	v_mul_f32_e32 v106, v237, v252
	v_fma_f32 v237, v236, v253, v106
	v_fma_f32 v236, v236, v252, -v105
	v_add_f32_e32 v110, v230, v232
	v_sub_f32_e32 v112, v230, v232
	v_add_f32_e32 v30, v234, v236
	v_sub_f32_e32 v32, v234, v236
	v_add_f32_e32 v111, v231, v233
	v_sub_f32_e32 v113, v231, v233
	v_add_f32_e32 v31, v235, v237
	v_sub_f32_e32 v33, v235, v237
	v_add_f32_e32 v230, v110, v30
	v_add_f32_e32 v231, v111, v31
	v_sub_f32_e32 v232, v112, v33
	v_add_f32_e32 v233, v113, v32
	v_sub_f32_e32 v234, v110, v30
	v_sub_f32_e32 v235, v111, v31
	v_add_f32_e32 v236, v112, v33
	v_sub_f32_e32 v237, v113, v32
	ds_write_b64 v72, v[230:231] offset:16384
	ds_write_b64 v73, v[232:233] offset:16384
	ds_write_b64 v74, v[234:235] offset:16384
	ds_write_b64 v75, v[236:237] offset:16384
	v_add_u32_e32 v72, 0x8000, v72
	v_add_u32_e32 v73, 0x8000, v73
	v_add_u32_e32 v74, 0x8000, v74
	v_add_u32_e32 v75, 0x8000, v75
	s_add_i32 s5, s5, -1
	s_cmp_lg_u32 s5, 0
	s_cbranch_scc1 .Lffu_fa_1
	s_branch .LBB0_704
.Lffs_fa_4:
	s_movk_i32 s0, 0x20
	s_movk_i32 s1, 0x40
	s_movk_i32 s4, 0x60
	v_and_b32_e32 v250, 3, v38
	v_sub_u32_e32 v251, v38, v250
	v_lshl_or_b32 v251, v251, 2, v250
	v_cvt_f32_u32_e32 v250, v250
	v_mul_f32_e32 v250, 0x3d800000, v250
	v_cos_f32_e32 v106, v250
	v_sin_f32_e32 v107, v250
	v_bfe_u32 v252, v251, 5, 2
	v_bfe_u32 v253, v251, 6, 1
	v_lshl_or_b32 v252, v252, 2, v252
	v_lshl_or_b32 v252, v253, 4, v252
	v_xor_b32_e32 v252, v252, v251
	v_lshlrev_b32_e32 v252, 3, v252
	v_add_u32_e32 v72, v40, v252
	v_xad_u32 v73, v252, s0, v40
	v_xad_u32 v74, v252, s1, v40
	v_xad_u32 v75, v252, s4, v40
	v_mul_f32_e32 v108, v107, v107
	v_mul_f32_e32 v109, v107, v106
	v_fma_f32 v108, v106, v106, -v108
	v_fma_f32 v109, v106, v107, v109
	ds_read_b64 v[64:65], v72
	ds_read_b64 v[66:67], v73
	ds_read_b64 v[68:69], v74
	ds_read_b64 v[70:71], v75
	s_mov_b32 s5, 4
	s_waitcnt lgkmcnt(0)
; DI float cos2pi(float x) { return __builtin_amdgcn_cosf(x); }
; DI float sin2pi(float x) { return __builtin_amdgcn_sinf(x); }
; template <bool INV>
; DI void fft_lds(float2* buf_, int L, int logL, int gtid, int NTG) {
;     ...
;       for (int t = gtid; t < (L >> 2); t += NTG) {
;         const int k = t & (S - 1), base = ((t - k) << 2) | k;
;         const v2f a0 = buf[base], a1 = buf[base + S], a2 = buf[base + 2 * S], a3 = buf[base + 3 * S];
;         const float fr = (float)k * i4;
;         const v2f w1 = v2f{cos2pi(fr), sin2pi(fr)};
;         const v2f w2 = vcmul(w1, w1);
;         const v2f x0 = a0 + a2;
;         const v2f x2 = vcmulc(a0 - a2, w1);
;         const v2f x1 = a1 + a3;
;         const v2f d13 = vcmulc(a1 - a3, w1);
;         const v2f x3 = v2f{d13.y, -d13.x};
;         buf[base] = x0 + x1;
;         buf[base + S] = vcmulc(x0 - x1, w2);
;         buf[base + 2 * S] = x2 + x3;
;         buf[base + 3 * S] = vcmulc(x2 - x3, w2);
;       }
.Lffl_fa_4:
	ds_read_b64 v[230:231], v72 offset:16384
	ds_read_b64 v[232:233], v73 offset:16384
	ds_read_b64 v[234:235], v74 offset:16384
	ds_read_b64 v[236:237], v75 offset:16384
	s_waitcnt lgkmcnt(8)
	v_add_f32_e32 v110, v64, v68
	v_sub_f32_e32 v112, v64, v68
	v_add_f32_e32 v30, v66, v70
	v_sub_f32_e32 v32, v66, v70
	v_add_f32_e32 v111, v65, v69
	v_sub_f32_e32 v113, v65, v69
	v_add_f32_e32 v31, v67, v71
	v_sub_f32_e32 v33, v67, v71
	v_mul_f32_e32 v251, v112, v106
	v_mul_f32_e32 v252, v112, v107
	v_fma_f32 v47, v113, v107, v251
	v_fma_f32 v250, v113, v106, -v252
	v_mul_f32_e32 v251, v32, v106
	v_mul_f32_e32 v252, v32, v107
	v_fma_f32 v253, v33, v107, v251
	v_fma_f32 v254, v33, v106, -v252
	v_add_f32_e32 v64, v110, v30
	v_add_f32_e32 v65, v111, v31
	v_sub_f32_e32 v110, v110, v30
	v_sub_f32_e32 v111, v111, v31
	v_mul_f32_e32 v251, v110, v108
	v_mul_f32_e32 v252, v110, v109
	v_fma_f32 v66, v111, v109, v251
	v_fma_f32 v67, v111, v108, -v252
	v_add_f32_e32 v68, v47, v254
	v_sub_f32_e32 v69, v250, v253
	v_sub_f32_e32 v30, v47, v254
	v_add_f32_e32 v31, v250, v253
	v_mul_f32_e32 v251, v30, v108
	v_mul_f32_e32 v252, v30, v109
	v_fma_f32 v70, v31, v109, v251
	v_fma_f32 v71, v31, v108, -v252
	ds_write_b64 v72, v[64:65]
	ds_write_b64 v73, v[66:67]
	ds_write_b64 v74, v[68:69]
	ds_write_b64 v75, v[70:71]
	ds_read_b64 v[64:65], v72 offset:32768
	ds_read_b64 v[66:67], v73 offset:32768
	ds_read_b64 v[68:69], v74 offset:32768
	ds_read_b64 v[70:71], v75 offset:32768
	s_waitcnt lgkmcnt(8)
	v_add_f32_e32 v110, v230, v234
	v_sub_f32_e32 v112, v230, v234
	v_add_f32_e32 v30, v232, v236
	v_sub_f32_e32 v32, v232, v236
	v_add_f32_e32 v111, v231, v235
	v_sub_f32_e32 v113, v231, v235
	v_add_f32_e32 v31, v233, v237
	v_sub_f32_e32 v33, v233, v237
	v_mul_f32_e32 v251, v112, v106
	v_mul_f32_e32 v252, v112, v107
	v_fma_f32 v47, v113, v107, v251
	v_fma_f32 v250, v113, v106, -v252
	v_mul_f32_e32 v251, v32, v106
	v_mul_f32_e32 v252, v32, v107
	v_fma_f32 v253, v33, v107, v251
	v_fma_f32 v254, v33, v106, -v252
	v_add_f32_e32 v230, v110, v30
	v_add_f32_e32 v231, v111, v31
	v_sub_f32_e32 v110, v110, v30
	v_sub_f32_e32 v111, v111, v31
	v_mul_f32_e32 v251, v110, v108
	v_mul_f32_e32 v252, v110, v109
	v_fma_f32 v232, v111, v109, v251
	v_fma_f32 v233, v111, v108, -v252
	v_add_f32_e32 v234, v47, v254
	v_sub_f32_e32 v235, v250, v253
	v_sub_f32_e32 v30, v47, v254
	v_add_f32_e32 v31, v250, v253
	v_mul_f32_e32 v251, v30, v108
	v_mul_f32_e32 v252, v30, v109
	v_fma_f32 v236, v31, v109, v251
	v_fma_f32 v237, v31, v108, -v252
	ds_write_b64 v72, v[230:231] offset:16384
	ds_write_b64 v73, v[232:233] offset:16384
	ds_write_b64 v74, v[234:235] offset:16384
	ds_write_b64 v75, v[236:237] offset:16384
	v_add_u32_e32 v72, 0x8000, v72
	v_add_u32_e32 v73, 0x8000, v73
	v_add_u32_e32 v74, 0x8000, v74
	v_add_u32_e32 v75, 0x8000, v75
	s_add_i32 s5, s5, -1
	s_cmp_lg_u32 s5, 0
	s_cbranch_scc1 .Lffl_fa_4
	s_branch .LBB0_704
.Lffs_fa_16:
	s_movk_i32 s0, 0x80
	s_movk_i32 s1, 0x128
	s_movk_i32 s4, 0x1a8
	v_and_b32_e32 v250, 15, v38
	v_sub_u32_e32 v251, v38, v250
	v_lshl_or_b32 v251, v251, 2, v250
	v_cvt_f32_u32_e32 v250, v250
	v_mul_f32_e32 v250, 0x3c800000, v250
	v_cos_f32_e32 v106, v250
	v_sin_f32_e32 v107, v250
	v_lshl_add_u32 v72, v251, 3, v40
	v_add_u32_e32 v73, 0x80, v72
	v_add_u32_e32 v74, 0x100, v72
	v_add_u32_e32 v75, 0x180, v72
	v_bfe_u32 v252, v251, 5, 2
	v_bfe_u32 v253, v251, 6, 1
	v_lshl_or_b32 v252, v252, 2, v252
	v_lshl_or_b32 v252, v253, 4, v252
	v_xor_b32_e32 v252, v252, v251
	v_lshlrev_b32_e32 v252, 3, v252
	v_add_u32_e32 v102, v40, v252
	v_xad_u32 v103, v252, s0, v40
	v_xad_u32 v104, v252, s1, v40
	v_xad_u32 v105, v252, s4, v40
	v_mul_f32_e32 v108, v107, v107
	v_mul_f32_e32 v109, v107, v106
	v_fma_f32 v108, v106, v106, -v108
	v_fma_f32 v109, v106, v107, v109
	ds_read_b64 v[64:65], v72
	ds_read_b64 v[66:67], v73
	ds_read_b64 v[68:69], v74
	ds_read_b64 v[70:71], v75
	s_mov_b32 s5, 4
	s_waitcnt lgkmcnt(0)
; DI float cos2pi(float x) { return __builtin_amdgcn_cosf(x); }
; DI float sin2pi(float x) { return __builtin_amdgcn_sinf(x); }
; template <bool INV>
; DI void fft_lds(float2* buf_, int L, int logL, int gtid, int NTG) {
;     ...
;       for (int t = gtid; t < (L >> 2); t += NTG) {
;         const int k = t & (S - 1), base = ((t - k) << 2) | k;
;         const v2f a0 = buf[base], a1 = buf[base + S], a2 = buf[base + 2 * S], a3 = buf[base + 3 * S];
;         const float fr = (float)k * i4;
;         const v2f w1 = v2f{cos2pi(fr), sin2pi(fr)};
;         const v2f w2 = vcmul(w1, w1);
;         const v2f x0 = a0 + a2;
;         const v2f x2 = vcmulc(a0 - a2, w1);
;         const v2f x1 = a1 + a3;
;         const v2f d13 = vcmulc(a1 - a3, w1);
;         const v2f x3 = v2f{d13.y, -d13.x};
;         buf[base] = x0 + x1;
;         buf[base + S] = vcmulc(x0 - x1, w2);
;         buf[base + 2 * S] = x2 + x3;
;         buf[base + 3 * S] = vcmulc(x2 - x3, w2);
;       }
.Lffl_fa_16:
	ds_read_b64 v[230:231], v72 offset:16384
	ds_read_b64 v[232:233], v73 offset:16384
	ds_read_b64 v[234:235], v74 offset:16384
	ds_read_b64 v[236:237], v75 offset:16384
	s_waitcnt lgkmcnt(8)
	v_add_f32_e32 v110, v64, v68
	v_sub_f32_e32 v112, v64, v68
	v_add_f32_e32 v30, v66, v70
	v_sub_f32_e32 v32, v66, v70
	v_add_f32_e32 v111, v65, v69
	v_sub_f32_e32 v113, v65, v69
	v_add_f32_e32 v31, v67, v71
	v_sub_f32_e32 v33, v67, v71
	v_mul_f32_e32 v251, v112, v106
	v_mul_f32_e32 v252, v112, v107
	v_fma_f32 v47, v113, v107, v251
	v_fma_f32 v250, v113, v106, -v252
	v_mul_f32_e32 v251, v32, v106
	v_mul_f32_e32 v252, v32, v107
	v_fma_f32 v253, v33, v107, v251
	v_fma_f32 v254, v33, v106, -v252
	v_add_f32_e32 v64, v110, v30
	v_add_f32_e32 v65, v111, v31
	v_sub_f32_e32 v110, v110, v30
	v_sub_f32_e32 v111, v111, v31
	v_mul_f32_e32 v251, v110, v108
	v_mul_f32_e32 v252, v110, v109
	v_fma_f32 v66, v111, v109, v251
	v_fma_f32 v67, v111, v108, -v252
	v_add_f32_e32 v68, v47, v254
	v_sub_f32_e32 v69, v250, v253
	v_sub_f32_e32 v30, v47, v254
	v_add_f32_e32 v31, v250, v253
	v_mul_f32_e32 v251, v30, v108
	v_mul_f32_e32 v252, v30, v109
	v_fma_f32 v70, v31, v109, v251
	v_fma_f32 v71, v31, v108, -v252
	ds_write_b64 v102, v[64:65]
	ds_write_b64 v103, v[66:67]
	ds_write_b64 v104, v[68:69]
	ds_write_b64 v105, v[70:71]
	ds_read_b64 v[64:65], v72 offset:32768
	ds_read_b64 v[66:67], v73 offset:32768
	ds_read_b64 v[68:69], v74 offset:32768
	ds_read_b64 v[70:71], v75 offset:32768
	s_waitcnt lgkmcnt(8)
	v_add_f32_e32 v110, v230, v234
	v_sub_f32_e32 v112, v230, v234
	v_add_f32_e32 v30, v232, v236
	v_sub_f32_e32 v32, v232, v236
	v_add_f32_e32 v111, v231, v235
	v_sub_f32_e32 v113, v231, v235
	v_add_f32_e32 v31, v233, v237
	v_sub_f32_e32 v33, v233, v237
	v_mul_f32_e32 v251, v112, v106
	v_mul_f32_e32 v252, v112, v107
	v_fma_f32 v47, v113, v107, v251
	v_fma_f32 v250, v113, v106, -v252
	v_mul_f32_e32 v251, v32, v106
	v_mul_f32_e32 v252, v32, v107
	v_fma_f32 v253, v33, v107, v251
	v_fma_f32 v254, v33, v106, -v252
	v_add_f32_e32 v230, v110, v30
	v_add_f32_e32 v231, v111, v31
	v_sub_f32_e32 v110, v110, v30
	v_sub_f32_e32 v111, v111, v31
	v_mul_f32_e32 v251, v110, v108
	v_mul_f32_e32 v252, v110, v109
	v_fma_f32 v232, v111, v109, v251
	v_fma_f32 v233, v111, v108, -v252
	v_add_f32_e32 v234, v47, v254
	v_sub_f32_e32 v235, v250, v253
	v_sub_f32_e32 v30, v47, v254
	v_add_f32_e32 v31, v250, v253
	v_mul_f32_e32 v251, v30, v108
	v_mul_f32_e32 v252, v30, v109
	v_fma_f32 v236, v31, v109, v251
	v_fma_f32 v237, v31, v108, -v252
	ds_write_b64 v102, v[230:231] offset:16384
	ds_write_b64 v103, v[232:233] offset:16384
	ds_write_b64 v104, v[234:235] offset:16384
	ds_write_b64 v105, v[236:237] offset:16384
	v_add_u32_e32 v72, 0x8000, v72
	v_add_u32_e32 v73, 0x8000, v73
	v_add_u32_e32 v74, 0x8000, v74
	v_add_u32_e32 v75, 0x8000, v75
	v_add_u32_e32 v102, 0x8000, v102
	v_add_u32_e32 v103, 0x8000, v103
	v_add_u32_e32 v104, 0x8000, v104
	v_add_u32_e32 v105, 0x8000, v105
	s_add_i32 s5, s5, -1
	s_cmp_lg_u32 s5, 0
	s_cbranch_scc1 .Lffl_fa_16
	s_branch .LBB0_704
.Lffs_fa_64:
	v_and_b32_e32 v250, 63, v38
	v_sub_u32_e32 v251, v38, v250
	v_lshl_or_b32 v251, v251, 2, v250
	v_cvt_f32_u32_e32 v250, v250
	v_mul_f32_e32 v250, 0x3b800000, v250
	v_cos_f32_e32 v106, v250
	v_sin_f32_e32 v107, v250
	v_lshl_add_u32 v72, v251, 3, v40
	v_add_u32_e32 v73, 0x200, v72
	v_add_u32_e32 v74, 0x400, v72
	v_add_u32_e32 v75, 0x600, v72
	v_mul_f32_e32 v108, v107, v107
	v_mul_f32_e32 v109, v107, v106
	v_fma_f32 v108, v106, v106, -v108
	v_fma_f32 v109, v106, v107, v109
	ds_read_b64 v[64:65], v72
	ds_read_b64 v[66:67], v73
	ds_read_b64 v[68:69], v74
	ds_read_b64 v[70:71], v75
	s_mov_b32 s5, 4
	s_waitcnt lgkmcnt(0)

; DI float cos2pi(float x) { return __builtin_amdgcn_cosf(x); }
; DI float sin2pi(float x) { return __builtin_amdgcn_sinf(x); }
; template <bool INV>
; DI void fft_lds(float2* buf_, int L, int logL, int gtid, int NTG) {
;     ...
;       for (int t = gtid; t < (L >> 2); t += NTG) {
;         const int k = t & (S - 1), base = ((t - k) << 2) | k;
;         const v2f a0 = buf[base], a1 = buf[base + S], a2 = buf[base + 2 * S], a3 = buf[base + 3 * S];
;         const float fr = (float)k * i4;
;         const v2f w1 = v2f{cos2pi(fr), sin2pi(fr)};
;         const v2f w2 = vcmul(w1, w1);
;         const v2f x0 = a0 + a2;
;         const v2f x2 = vcmulc(a0 - a2, w1);
;         const v2f x1 = a1 + a3;
;         const v2f d13 = vcmulc(a1 - a3, w1);
;         const v2f x3 = v2f{d13.y, -d13.x};
;         buf[base] = x0 + x1;
;         buf[base + S] = vcmulc(x0 - x1, w2);
;         buf[base + 2 * S] = x2 + x3;
;         buf[base + 3 * S] = vcmulc(x2 - x3, w2);
;       }
.Lffs_fa_256:
	v_and_b32_e32 v250, 255, v38
	v_sub_u32_e32 v251, v38, v250
	v_lshl_or_b32 v251, v251, 2, v250
	v_cvt_f32_u32_e32 v250, v250
	v_mul_f32_e32 v250, 0x3a800000, v250
	v_cos_f32_e32 v106, v250
	v_sin_f32_e32 v107, v250
	v_lshl_add_u32 v72, v251, 3, v40
	v_add_u32_e32 v73, 0x800, v72
	v_add_u32_e32 v74, 0x1000, v72
	v_add_u32_e32 v75, 0x1800, v72
	v_mul_f32_e32 v108, v107, v107
	v_mul_f32_e32 v109, v107, v106
	v_fma_f32 v108, v106, v106, -v108
	v_fma_f32 v109, v106, v107, v109
	ds_read_b64 v[64:65], v72
	ds_read_b64 v[66:67], v73
	ds_read_b64 v[68:69], v74
	ds_read_b64 v[70:71], v75
	s_mov_b32 s5, 4
	s_waitcnt lgkmcnt(0)
.Lffl_fa_256:
	ds_read_b64 v[230:231], v72 offset:16384
	ds_read_b64 v[232:233], v73 offset:16384
	ds_read_b64 v[234:235], v74 offset:16384
	ds_read_b64 v[236:237], v75 offset:16384
	s_waitcnt lgkmcnt(8)
	v_add_f32_e32 v110, v64, v68
	v_sub_f32_e32 v112, v64, v68
	v_add_f32_e32 v30, v66, v70
	v_sub_f32_e32 v32, v66, v70
	v_add_f32_e32 v111, v65, v69
	v_sub_f32_e32 v113, v65, v69
	v_add_f32_e32 v31, v67, v71
	v_sub_f32_e32 v33, v67, v71
	v_mul_f32_e32 v251, v112, v106
	v_mul_f32_e32 v252, v112, v107
	v_fma_f32 v47, v113, v107, v251
	v_fma_f32 v250, v113, v106, -v252
	v_mul_f32_e32 v251, v32, v106
	v_mul_f32_e32 v252, v32, v107
	v_fma_f32 v253, v33, v107, v251
	v_fma_f32 v254, v33, v106, -v252
	v_add_f32_e32 v64, v110, v30
	v_add_f32_e32 v65, v111, v31
	v_sub_f32_e32 v110, v110, v30
	v_sub_f32_e32 v111, v111, v31
	v_mul_f32_e32 v251, v110, v108
	v_mul_f32_e32 v252, v110, v109
	v_fma_f32 v66, v111, v109, v251
	v_fma_f32 v67, v111, v108, -v252
	v_add_f32_e32 v68, v47, v254
	v_sub_f32_e32 v69, v250, v253
	v_sub_f32_e32 v30, v47, v254
	v_add_f32_e32 v31, v250, v253
	v_mul_f32_e32 v251, v30, v108
	v_mul_f32_e32 v252, v30, v109
	v_fma_f32 v70, v31, v109, v251
	v_fma_f32 v71, v31, v108, -v252
	ds_write_b64 v72, v[64:65]
	ds_write_b64 v73, v[66:67]
	ds_write_b64 v74, v[68:69]
	ds_write_b64 v75, v[70:71]
	ds_read_b64 v[64:65], v72 offset:32768
	ds_read_b64 v[66:67], v73 offset:32768
	ds_read_b64 v[68:69], v74 offset:32768
	ds_read_b64 v[70:71], v75 offset:32768
	s_waitcnt lgkmcnt(8)
	v_add_f32_e32 v110, v230, v234
	v_sub_f32_e32 v112, v230, v234
	v_add_f32_e32 v30, v232, v236
	v_sub_f32_e32 v32, v232, v236
	v_add_f32_e32 v111, v231, v235
	v_sub_f32_e32 v113, v231, v235
	v_add_f32_e32 v31, v233, v237
	v_sub_f32_e32 v33, v233, v237
	v_mul_f32_e32 v251, v112, v106
	v_mul_f32_e32 v252, v112, v107
	v_fma_f32 v47, v113, v107, v251
	v_fma_f32 v250, v113, v106, -v252
	v_mul_f32_e32 v251, v32, v106
	v_mul_f32_e32 v252, v32, v107
	v_fma_f32 v253, v33, v107, v251
	v_fma_f32 v254, v33, v106, -v252
	v_add_f32_e32 v230, v110, v30
	v_add_f32_e32 v231, v111, v31
	v_sub_f32_e32 v110, v110, v30
	v_sub_f32_e32 v111, v111, v31
	v_mul_f32_e32 v251, v110, v108
	v_mul_f32_e32 v252, v110, v109
	v_fma_f32 v232, v111, v109, v251
	v_fma_f32 v233, v111, v108, -v252
	v_add_f32_e32 v234, v47, v254
	v_sub_f32_e32 v235, v250, v253
	v_sub_f32_e32 v30, v47, v254
	v_add_f32_e32 v31, v250, v253
	v_mul_f32_e32 v251, v30, v108
	v_mul_f32_e32 v252, v30, v109
	v_fma_f32 v236, v31, v109, v251
	v_fma_f32 v237, v31, v108, -v252
	ds_write_b64 v72, v[230:231] offset:16384
	ds_write_b64 v73, v[232:233] offset:16384
	ds_write_b64 v74, v[234:235] offset:16384
	ds_write_b64 v75, v[236:237] offset:16384
	v_add_u32_e32 v72, 0x8000, v72
	v_add_u32_e32 v73, 0x8000, v73
	v_add_u32_e32 v74, 0x8000, v74
	v_add_u32_e32 v75, 0x8000, v75
	s_add_i32 s5, s5, -1
	s_cmp_lg_u32 s5, 0
	s_cbranch_scc1 .Lffl_fa_256
	s_branch .LBB0_704
	s_branch .Lffs_f_skip

; DI float cos2pi(float x) { return __builtin_amdgcn_cosf(x); }
; DI float sin2pi(float x) { return __builtin_amdgcn_sinf(x); }
; DI float2 cmul(float2 a, float2 b) { return make_float2(a.x * b.x - a.y * b.y, a.x * b.y + a.y * b.x); }
; template <bool INV>
; DI void fft_lds(float2* buf_, int L, int logL, int gtid, int NTG) {
;     ...
;       for (int t = gtid; t < (L >> 2); t += NTG) {
;         const int k = t & (S - 1), base = ((t - k) << 2) | k;
;         const v2f a0 = buf[base], a1 = buf[base + S], a2 = buf[base + 2 * S], a3 = buf[base + 3 * S];
;         const float fr = (float)k * i4;
;         const v2f w1 = v2f{cos2pi(fr), sin2pi(fr)};
;         const v2f w2 = vcmul(w1, w1);
;         const v2f x0 = a0 + a2;
;         const v2f x2 = vcmulc(a0 - a2, w1);
;         const v2f x1 = a1 + a3;
;         const v2f d13 = vcmulc(a1 - a3, w1);
;         const v2f x3 = v2f{d13.y, -d13.x};
;         buf[base] = x0 + x1;
;         buf[base + S] = vcmulc(x0 - x1, w2);
;         buf[base + 2 * S] = x2 + x3;
;         buf[base + 3 * S] = vcmulc(x2 - x3, w2);
;       }
;     ...
;       for (int t = gtid; t < (L >> 2); t += NTG) {
;         const int k = t & (S - 1), base = ((t - k) << 2) | k;
;         const v2f p0 = buf[base], p1 = buf[base + S], p2 = buf[base + 2 * S], p3 = buf[base + 3 * S];
;         const float fr = (float)k * i4;
;         const v2f w1 = v2f{cos2pi(fr), sin2pi(fr)};
;         const v2f w2 = vcmul(w1, w1);
;         const v2f b1 = vcmul(p1, w2), b3 = vcmul(p3, w2);
;         const v2f q0 = p0 + b1, q1 = p0 - b1, q2 = p2 + b3, q3 = p2 - b3;
;         const v2f c2 = vcmul(q2, w1);
;         const v2f t3 = vcmul(q3, w1); const v2f c3 = v2f{-t3.y, t3.x};
;         buf[base] = q0 + c2;
;         buf[base + 2 * S] = q0 - c2;
;         buf[base + S] = q1 + c3;
;         buf[base + 3 * S] = q1 - c3;
;       }
; DI void hyena_item(const Ctx& c, int ch, float* red) {
;     ...
;         for (int n = gtid; n < L; n += NTG) bufg[n] = cmul(bufg[n], SPEC[p * 16384 + n]);
.Lffs_f_n64:
	s_cmp_gt_u32 s82, 64
	s_cbranch_scc1 .Lffs_fb_skip
	s_cmp_eq_u32 s82, 64
	s_cbranch_scc1 .Lffs_fb_64
	s_cmp_eq_u32 s82, 16
	s_cbranch_scc1 .Lffs_fb_16
	s_cmp_eq_u32 s82, 4
	s_cbranch_scc1 .Lffs_fb_4
	s_mov_b32 s0, 0x800
	s_mov_b32 s1, 0
	v_lshlrev_b32_e32 v104, 2, v38
	v_add_u32_e32 v102, s24, v104
	v_ashrrev_i32_e32 v103, 31, v102
	v_lshl_add_u64 v[102:103], v[102:103], 3, s[2:3]
	v_bfe_u32 v105, v104, 5, 2
	v_bfe_u32 v106, v104, 6, 1
	v_lshl_or_b32 v105, v105, 2, v105
	v_lshl_or_b32 v105, v106, 4, v105
	v_xor_b32_e32 v105, v105, v104
	v_lshlrev_b32_e32 v105, 3, v105
	v_add_u32_e32 v72, v40, v105
	v_xad_u32 v73, v105, 8, v40
	v_xad_u32 v74, v105, 16, v40
	v_xad_u32 v75, v105, 24, v40
	s_mov_b32 s5, 4
.Lffu_fb_1:
	global_load_dwordx4 v[238:241], v[102:103], off
	global_load_dwordx4 v[242:245], v[102:103], off offset:16
	v_lshl_add_u64 v[102:103], v[102:103], 0, s[0:1]
	global_load_dwordx4 v[246:249], v[102:103], off
	global_load_dwordx4 v[250:253], v[102:103], off offset:16
	v_lshl_add_u64 v[102:103], v[102:103], 0, s[0:1]
	ds_read_b64 v[64:65], v72
	ds_read_b64 v[66:67], v73
	ds_read_b64 v[68:69], v74
	ds_read_b64 v[70:71], v75
	ds_read_b64 v[230:231], v72 offset:2048
	ds_read_b64 v[232:233], v73 offset:2048
	ds_read_b64 v[234:235], v74 offset:2048
	ds_read_b64 v[236:237], v75 offset:2048
	s_waitcnt lgkmcnt(4)
	v_add_f32_e32 v110, v64, v68
	v_sub_f32_e32 v112, v64, v68
	v_add_f32_e32 v30, v66, v70
	v_sub_f32_e32 v32, v66, v70
	v_add_f32_e32 v111, v65, v69
	v_sub_f32_e32 v113, v65, v69
	v_add_f32_e32 v31, v67, v71
	v_sub_f32_e32 v33, v67, v71
	v_add_f32_e32 v64, v110, v30
	v_add_f32_e32 v65, v111, v31
	v_sub_f32_e32 v66, v110, v30
	v_sub_f32_e32 v67, v111, v31
	v_add_f32_e32 v68, v112, v33
	v_sub_f32_e32 v69, v113, v32
	v_sub_f32_e32 v70, v112, v33
	v_add_f32_e32 v71, v113, v32
	s_waitcnt lgkmcnt(0)
	v_add_f32_e32 v110, v230, v234
	v_sub_f32_e32 v112, v230, v234
	v_add_f32_e32 v30, v232, v236
	v_sub_f32_e32 v32, v232, v236
	v_add_f32_e32 v111, v231, v235
	v_sub_f32_e32 v113, v231, v235
	v_add_f32_e32 v31, v233, v237
	v_sub_f32_e32 v33, v233, v237
	v_add_f32_e32 v230, v110, v30
	v_add_f32_e32 v231, v111, v31
	v_sub_f32_e32 v232, v110, v30
	v_sub_f32_e32 v233, v111, v31
	v_add_f32_e32 v234, v112, v33
	v_sub_f32_e32 v235, v113, v32
	v_sub_f32_e32 v236, v112, v33
	v_add_f32_e32 v237, v113, v32
	s_waitcnt vmcnt(2)
	v_mul_f32_e32 v47, v65, v239
	v_mul_f32_e32 v104, v65, v238
	v_fma_f32 v65, v64, v239, v104
	v_fma_f32 v64, v64, v238, -v47
	v_mul_f32_e32 v105, v67, v241
	v_mul_f32_e32 v106, v67, v240
	v_fma_f32 v67, v66, v241, v106
	v_fma_f32 v66, v66, v240, -v105
	v_mul_f32_e32 v47, v69, v243
	v_mul_f32_e32 v104, v69, v242
	v_fma_f32 v69, v68, v243, v104
	v_fma_f32 v68, v68, v242, -v47
	v_mul_f32_e32 v105, v71, v245
	v_mul_f32_e32 v106, v71, v244
	v_fma_f32 v71, v70, v245, v106
	v_fma_f32 v70, v70, v244, -v105
	v_add_f32_e32 v110, v64, v66
	v_sub_f32_e32 v112, v64, v66
	v_add_f32_e32 v30, v68, v70
	v_sub_f32_e32 v32, v68, v70
	v_add_f32_e32 v111, v65, v67
	v_sub_f32_e32 v113, v65, v67
	v_add_f32_e32 v31, v69, v71
	v_sub_f32_e32 v33, v69, v71
	v_add_f32_e32 v64, v110, v30
	v_add_f32_e32 v65, v111, v31
	v_sub_f32_e32 v66, v112, v33
	v_add_f32_e32 v67, v113, v32
	v_sub_f32_e32 v68, v110, v30
	v_sub_f32_e32 v69, v111, v31
	v_add_f32_e32 v70, v112, v33
	v_sub_f32_e32 v71, v113, v32
	ds_write_b64 v72, v[64:65]
	ds_write_b64 v73, v[66:67]
	ds_write_b64 v74, v[68:69]
	ds_write_b64 v75, v[70:71]
	s_waitcnt vmcnt(0)
	v_mul_f32_e32 v47, v231, v247
	v_mul_f32_e32 v104, v231, v246
	v_fma_f32 v231, v230, v247, v104
	v_fma_f32 v230, v230, v246, -v47
	v_mul_f32_e32 v105, v233, v249
	v_mul_f32_e32 v106, v233, v248
	v_fma_f32 v233, v232, v249, v106
	v_fma_f32 v232, v232, v248, -v105
	v_mul_f32_e32 v47, v235, v251
	v_mul_f32_e32 v104, v235, v250
	v_fma_f32 v235, v234, v251, v104
	v_fma_f32 v234, v234, v250, -v47
	v_mul_f32_e32 v105, v237, v253
	v_mul_f32_e32 v106, v237, v252
	v_fma_f32 v237, v236, v253, v106
	v_fma_f32 v236, v236, v252, -v105
	v_add_f32_e32 v110, v230, v232
	v_sub_f32_e32 v112, v230, v232
	v_add_f32_e32 v30, v234, v236
	v_sub_f32_e32 v32, v234, v236
	v_add_f32_e32 v111, v231, v233
	v_sub_f32_e32 v113, v231, v233
	v_add_f32_e32 v31, v235, v237
	v_sub_f32_e32 v33, v235, v237
	v_add_f32_e32 v230, v110, v30
	v_add_f32_e32 v231, v111, v31
	v_sub_f32_e32 v232, v112, v33
	v_add_f32_e32 v233, v113, v32
	v_sub_f32_e32 v234, v110, v30
	v_sub_f32_e32 v235, v111, v31
	v_add_f32_e32 v236, v112, v33
	v_sub_f32_e32 v237, v113, v32
	ds_write_b64 v72, v[230:231] offset:2048
	ds_write_b64 v73, v[232:233] offset:2048
	ds_write_b64 v74, v[234:235] offset:2048
	ds_write_b64 v75, v[236:237] offset:2048
	v_add_u32_e32 v72, 0x1000, v72
	v_add_u32_e32 v73, 0x1000, v73
	v_add_u32_e32 v74, 0x1000, v74
	v_add_u32_e32 v75, 0x1000, v75
	s_add_i32 s5, s5, -1
	s_cmp_lg_u32 s5, 0
	s_cbranch_scc1 .Lffu_fb_1
	s_branch .LBB0_704

; DI float cos2pi(float x) { return __builtin_amdgcn_cosf(x); }
; DI float sin2pi(float x) { return __builtin_amdgcn_sinf(x); }
; template <bool INV>
; DI void fft_lds(float2* buf_, int L, int logL, int gtid, int NTG) {
;     ...
;       for (int t = gtid; t < (L >> 2); t += NTG) {
;         const int k = t & (S - 1), base = ((t - k) << 2) | k;
;         const v2f a0 = buf[base], a1 = buf[base + S], a2 = buf[base + 2 * S], a3 = buf[base + 3 * S];
;         const float fr = (float)k * i4;
;         const v2f w1 = v2f{cos2pi(fr), sin2pi(fr)};
;         const v2f w2 = vcmul(w1, w1);
;         const v2f x0 = a0 + a2;
;         const v2f x2 = vcmulc(a0 - a2, w1);
;         const v2f x1 = a1 + a3;
;         const v2f d13 = vcmulc(a1 - a3, w1);
;         const v2f x3 = v2f{d13.y, -d13.x};
;         buf[base] = x0 + x1;
;         buf[base + S] = vcmulc(x0 - x1, w2);
;         buf[base + 2 * S] = x2 + x3;
;         buf[base + 3 * S] = vcmulc(x2 - x3, w2);
;       }
.Lffl_fb_4:
	ds_read_b64 v[230:231], v72 offset:2048
	ds_read_b64 v[232:233], v73 offset:2048
	ds_read_b64 v[234:235], v74 offset:2048
	ds_read_b64 v[236:237], v75 offset:2048
	s_waitcnt lgkmcnt(8)
	v_add_f32_e32 v110, v64, v68
	v_sub_f32_e32 v112, v64, v68
	v_add_f32_e32 v30, v66, v70
	v_sub_f32_e32 v32, v66, v70
	v_add_f32_e32 v111, v65, v69
	v_sub_f32_e32 v113, v65, v69
	v_add_f32_e32 v31, v67, v71
	v_sub_f32_e32 v33, v67, v71
	v_mul_f32_e32 v251, v112, v106
	v_mul_f32_e32 v252, v112, v107
	v_fma_f32 v47, v113, v107, v251
	v_fma_f32 v250, v113, v106, -v252
	v_mul_f32_e32 v251, v32, v106
	v_mul_f32_e32 v252, v32, v107
	v_fma_f32 v253, v33, v107, v251
	v_fma_f32 v254, v33, v106, -v252
	v_add_f32_e32 v64, v110, v30
	v_add_f32_e32 v65, v111, v31
	v_sub_f32_e32 v110, v110, v30
	v_sub_f32_e32 v111, v111, v31
	v_mul_f32_e32 v251, v110, v108
	v_mul_f32_e32 v252, v110, v109
	v_fma_f32 v66, v111, v109, v251
	v_fma_f32 v67, v111, v108, -v252
	v_add_f32_e32 v68, v47, v254
	v_sub_f32_e32 v69, v250, v253
	v_sub_f32_e32 v30, v47, v254
	v_add_f32_e32 v31, v250, v253
	v_mul_f32_e32 v251, v30, v108
	v_mul_f32_e32 v252, v30, v109
	v_fma_f32 v70, v31, v109, v251
	v_fma_f32 v71, v31, v108, -v252
	ds_write_b64 v72, v[64:65]
	ds_write_b64 v73, v[66:67]
	ds_write_b64 v74, v[68:69]
	ds_write_b64 v75, v[70:71]
	ds_read_b64 v[64:65], v72 offset:4096
	ds_read_b64 v[66:67], v73 offset:4096
	ds_read_b64 v[68:69], v74 offset:4096
	ds_read_b64 v[70:71], v75 offset:4096
	s_waitcnt lgkmcnt(8)
	v_add_f32_e32 v110, v230, v234
	v_sub_f32_e32 v112, v230, v234
	v_add_f32_e32 v30, v232, v236
	v_sub_f32_e32 v32, v232, v236
	v_add_f32_e32 v111, v231, v235
	v_sub_f32_e32 v113, v231, v235
	v_add_f32_e32 v31, v233, v237
	v_sub_f32_e32 v33, v233, v237
	v_mul_f32_e32 v251, v112, v106
	v_mul_f32_e32 v252, v112, v107
	v_fma_f32 v47, v113, v107, v251
	v_fma_f32 v250, v113, v106, -v252
	v_mul_f32_e32 v251, v32, v106
	v_mul_f32_e32 v252, v32, v107
	v_fma_f32 v253, v33, v107, v251
	v_fma_f32 v254, v33, v106, -v252
	v_add_f32_e32 v230, v110, v30
	v_add_f32_e32 v231, v111, v31
	v_sub_f32_e32 v110, v110, v30
	v_sub_f32_e32 v111, v111, v31
	v_mul_f32_e32 v251, v110, v108
	v_mul_f32_e32 v252, v110, v109
	v_fma_f32 v232, v111, v109, v251
	v_fma_f32 v233, v111, v108, -v252
	v_add_f32_e32 v234, v47, v254
	v_sub_f32_e32 v235, v250, v253
	v_sub_f32_e32 v30, v47, v254
	v_add_f32_e32 v31, v250, v253
	v_mul_f32_e32 v251, v30, v108
	v_mul_f32_e32 v252, v30, v109
	v_fma_f32 v236, v31, v109, v251
	v_fma_f32 v237, v31, v108, -v252
	ds_write_b64 v72, v[230:231] offset:2048
	ds_write_b64 v73, v[232:233] offset:2048
	ds_write_b64 v74, v[234:235] offset:2048
	ds_write_b64 v75, v[236:237] offset:2048
	v_add_u32_e32 v72, 0x1000, v72
	v_add_u32_e32 v73, 0x1000, v73
	v_add_u32_e32 v74, 0x1000, v74
	v_add_u32_e32 v75, 0x1000, v75
	s_add_i32 s5, s5, -1
	s_cmp_lg_u32 s5, 0
	s_cbranch_scc1 .Lffl_fb_4
	s_branch .LBB0_704

; DI float cos2pi(float x) { return __builtin_amdgcn_cosf(x); }
; DI float sin2pi(float x) { return __builtin_amdgcn_sinf(x); }
; template <bool INV>
; DI void fft_lds(float2* buf_, int L, int logL, int gtid, int NTG) {
;     ...
;       for (int t = gtid; t < (L >> 2); t += NTG) {
;         const int k = t & (S - 1), base = ((t - k) << 2) | k;
;         const v2f a0 = buf[base], a1 = buf[base + S], a2 = buf[base + 2 * S], a3 = buf[base + 3 * S];
;         const float fr = (float)k * i4;
;         const v2f w1 = v2f{cos2pi(fr), sin2pi(fr)};
;         const v2f w2 = vcmul(w1, w1);
;         const v2f x0 = a0 + a2;
;         const v2f x2 = vcmulc(a0 - a2, w1);
;         const v2f x1 = a1 + a3;
;         const v2f d13 = vcmulc(a1 - a3, w1);
;         const v2f x3 = v2f{d13.y, -d13.x};
;         buf[base] = x0 + x1;
;         buf[base + S] = vcmulc(x0 - x1, w2);
;         buf[base + 2 * S] = x2 + x3;
;         buf[base + 3 * S] = vcmulc(x2 - x3, w2);
;       }
.Lffl_fb_16:
	ds_read_b64 v[230:231], v72 offset:2048
	ds_read_b64 v[232:233], v73 offset:2048
	ds_read_b64 v[234:235], v74 offset:2048
	ds_read_b64 v[236:237], v75 offset:2048
	s_waitcnt lgkmcnt(8)
	v_add_f32_e32 v110, v64, v68
	v_sub_f32_e32 v112, v64, v68
	v_add_f32_e32 v30, v66, v70
	v_sub_f32_e32 v32, v66, v70
	v_add_f32_e32 v111, v65, v69
	v_sub_f32_e32 v113, v65, v69
	v_add_f32_e32 v31, v67, v71
	v_sub_f32_e32 v33, v67, v71
	v_mul_f32_e32 v251, v112, v106
	v_mul_f32_e32 v252, v112, v107
	v_fma_f32 v47, v113, v107, v251
	v_fma_f32 v250, v113, v106, -v252
	v_mul_f32_e32 v251, v32, v106
	v_mul_f32_e32 v252, v32, v107
	v_fma_f32 v253, v33, v107, v251
	v_fma_f32 v254, v33, v106, -v252
	v_add_f32_e32 v64, v110, v30
	v_add_f32_e32 v65, v111, v31
	v_sub_f32_e32 v110, v110, v30
	v_sub_f32_e32 v111, v111, v31
	v_mul_f32_e32 v251, v110, v108
	v_mul_f32_e32 v252, v110, v109
	v_fma_f32 v66, v111, v109, v251
	v_fma_f32 v67, v111, v108, -v252
	v_add_f32_e32 v68, v47, v254
	v_sub_f32_e32 v69, v250, v253
	v_sub_f32_e32 v30, v47, v254
	v_add_f32_e32 v31, v250, v253
	v_mul_f32_e32 v251, v30, v108
	v_mul_f32_e32 v252, v30, v109
	v_fma_f32 v70, v31, v109, v251
	v_fma_f32 v71, v31, v108, -v252
	ds_write_b64 v102, v[64:65]
	ds_write_b64 v103, v[66:67]
	ds_write_b64 v104, v[68:69]
	ds_write_b64 v105, v[70:71]
	ds_read_b64 v[64:65], v72 offset:4096
	ds_read_b64 v[66:67], v73 offset:4096
	ds_read_b64 v[68:69], v74 offset:4096
	ds_read_b64 v[70:71], v75 offset:4096
	s_waitcnt lgkmcnt(8)
	v_add_f32_e32 v110, v230, v234
	v_sub_f32_e32 v112, v230, v234
	v_add_f32_e32 v30, v232, v236
	v_sub_f32_e32 v32, v232, v236
	v_add_f32_e32 v111, v231, v235
	v_sub_f32_e32 v113, v231, v235
	v_add_f32_e32 v31, v233, v237
	v_sub_f32_e32 v33, v233, v237
	v_mul_f32_e32 v251, v112, v106
	v_mul_f32_e32 v252, v112, v107
	v_fma_f32 v47, v113, v107, v251
	v_fma_f32 v250, v113, v106, -v252
	v_mul_f32_e32 v251, v32, v106
	v_mul_f32_e32 v252, v32, v107
	v_fma_f32 v253, v33, v107, v251
	v_fma_f32 v254, v33, v106, -v252
	v_add_f32_e32 v230, v110, v30
	v_add_f32_e32 v231, v111, v31
	v_sub_f32_e32 v110, v110, v30
	v_sub_f32_e32 v111, v111, v31
	v_mul_f32_e32 v251, v110, v108
	v_mul_f32_e32 v252, v110, v109
	v_fma_f32 v232, v111, v109, v251
	v_fma_f32 v233, v111, v108, -v252
	v_add_f32_e32 v234, v47, v254
	v_sub_f32_e32 v235, v250, v253
	v_sub_f32_e32 v30, v47, v254
	v_add_f32_e32 v31, v250, v253
	v_mul_f32_e32 v251, v30, v108
	v_mul_f32_e32 v252, v30, v109
	v_fma_f32 v236, v31, v109, v251
	v_fma_f32 v237, v31, v108, -v252
	ds_write_b64 v102, v[230:231] offset:2048
	ds_write_b64 v103, v[232:233] offset:2048
	ds_write_b64 v104, v[234:235] offset:2048
	ds_write_b64 v105, v[236:237] offset:2048
	v_add_u32_e32 v72, 0x1000, v72
	v_add_u32_e32 v73, 0x1000, v73
	v_add_u32_e32 v74, 0x1000, v74
	v_add_u32_e32 v75, 0x1000, v75
	v_add_u32_e32 v102, 0x1000, v102
	v_add_u32_e32 v103, 0x1000, v103
	v_add_u32_e32 v104, 0x1000, v104
	v_add_u32_e32 v105, 0x1000, v105
	s_add_i32 s5, s5, -1
	s_cmp_lg_u32 s5, 0
	s_cbranch_scc1 .Lffl_fb_16
	s_branch .LBB0_704

; template <bool INV>
; DI void fft_lds(float2* buf_, int L, int logL, int gtid, int NTG) {
;     ...
;     for (; s >= 2; s >>= 2) {
;       const int S = s >> 1;
;       const float i4 = 0.25f / (float)S;
; #pragma unroll 8
;       for (int t = gtid; t < (L >> 2); t += NTG) {
;         const int k = t & (S - 1), base = ((t - k) << 2) | k;
.Lffs_fb_skip:
.Lffs_f_skip:
	v_cvt_f32_u32_e32 v30, s82
	s_and_b32 s4, s6, 0x7ffffffe
	s_add_i32 s7, s82, -1
	v_div_scale_f32 v31, s[0:1], v30, v30, s60
	v_rcp_f32_e32 v32, v31
	v_div_scale_f32 v33, vcc, s60, v30, s60
	v_fma_f32 v47, -v31, v32, 1.0
	v_fmac_f32_e32 v32, v47, v32
	v_mul_f32_e32 v47, v33, v32
	v_fma_f32 v64, -v31, v47, v33
	v_fmac_f32_e32 v47, v64, v32
	v_fma_f32 v31, -v31, v47, v33
	v_div_fmas_f32 v31, v31, v32, v47
	v_div_fixup_f32 v32, v31, v30, s60
	v_lshl_add_u32 v33, s82, 3, v40
	v_lshl_add_u32 v47, s4, 3, v40
	v_mov_b32_e32 v64, v38
	s_and_saveexec_b64 s[0:1], s[48:49]
	s_cbranch_execz .LBB0_710
	v_mad_u64_u32 v[30:31], s[4:5], s82, 24, v[40:41]
	s_mov_b64 s[4:5], 0
	v_mov_b32_e32 v31, v90
	v_mov_b32_e32 v65, v101
	v_mov_b32_e32 v64, v38

; DI float2 cmul(float2 a, float2 b) { return make_float2(a.x * b.x - a.y * b.y, a.x * b.y + a.y * b.x); }
; DI void hyena_item(const Ctx& c, int ch, float* red) {
;     ...
; #pragma unroll 4
;         for (int n = gtid; n < L; n += NTG) bufg[n] = cmul(bufg[n], SPEC[p * 16384 + n]);
;         __syncthreads();
.LBB0_713:
	s_mov_b64 s[0:1], exec
	s_branch .LBB0_721
	v_mov_b32_e32 v32, v38
	s_and_saveexec_b64 s[4:5], s[20:21]
	s_cbranch_execz .LBB0_718
	v_add_u32_e32 v30, s24, v38
	v_ashrrev_i32_e32 v31, 31, v30
	v_lshl_add_u64 v[30:31], v[30:31], 3, s[2:3]
	s_mov_b64 s[54:55], 0
	v_mov_b32_e32 v33, v86
	v_mov_b32_e32 v47, v99
	v_mov_b32_e32 v32, v38

; template <bool INV>
; DI void fft_lds(float2* buf_, int L, int logL, int gtid, int NTG) {
;     ...
;     int S = 1;
;     const int nf = logL >> 1;
;     for (int f = 0; f < nf; ++f, S <<= 2) {
.LBB0_721:
	s_or_b64 exec, exec, s[0:1]
	s_mov_b32 s6, 1
	s_mov_b32 s7, 4
	s_waitcnt lgkmcnt(0)
	s_barrier
	s_branch .LBB0_723

; DI float cos2pi(float x) { return __builtin_amdgcn_cosf(x); }
; DI float sin2pi(float x) { return __builtin_amdgcn_sinf(x); }
; template <bool INV>
; DI void fft_lds(float2* buf_, int L, int logL, int gtid, int NTG) {
;     ...
;     for (int f = 0; f < nf; ++f, S <<= 2) {
;       const float i4 = 0.25f / (float)S;
; #pragma unroll 8
;       for (int t = gtid; t < (L >> 2); t += NTG) {
;         const int k = t & (S - 1), base = ((t - k) << 2) | k;
;         const v2f p0 = buf[base], p1 = buf[base + S], p2 = buf[base + 2 * S], p3 = buf[base + 3 * S];
;         const float fr = (float)k * i4;
;         const v2f w1 = v2f{cos2pi(fr), sin2pi(fr)};
;         const v2f w2 = vcmul(w1, w1);
;         const v2f b1 = vcmul(p1, w2), b3 = vcmul(p3, w2);
;         const v2f q0 = p0 + b1, q1 = p0 - b1, q2 = p2 + b3, q3 = p2 - b3;
;         const v2f c2 = vcmul(q2, w1);
;         const v2f t3 = vcmul(q3, w1); const v2f c3 = v2f{-t3.y, t3.x};
;         buf[base] = q0 + c2;
;         buf[base + 2 * S] = q0 - c2;
;         buf[base + S] = q1 + c3;
;         buf[base + 3 * S] = q1 - c3;
;       }
;       __syncthreads();
.LBB0_723:
	s_and_saveexec_b64 s[54:55], s[18:19]
	s_cbranch_execz .LBB0_722
	s_cmp_eq_u32 s61, 64
	s_cbranch_scc1 .Lffs_i_n64
	s_cmp_gt_u32 s7, 256
	s_cbranch_scc1 .Lffs_ia_skip
	s_cmp_eq_u32 s7, 256
	s_cbranch_scc1 .Lffs_ia_256
	s_cmp_eq_u32 s7, 64
	s_cbranch_scc1 .Lffs_ia_64
	s_cmp_eq_u32 s7, 16
	s_cbranch_scc1 .Lffs_ia_16
	s_cmp_eq_u32 s7, 4
	s_cbranch_scc1 .Lffs_ia_4
	s_movk_i32 s0, 0x8
	s_movk_i32 s1, 0x10
	s_movk_i32 s4, 0x18
	v_lshlrev_b32_e32 v251, 2, v38
	v_lshl_add_u32 v72, v251, 3, v40
	v_bfe_u32 v252, v251, 5, 2
	v_bfe_u32 v253, v251, 6, 1
	v_lshl_or_b32 v252, v252, 2, v252
	v_lshl_or_b32 v252, v253, 4, v252
	v_xor_b32_e32 v252, v252, v251
	v_lshlrev_b32_e32 v252, 3, v252
	v_add_u32_e32 v102, v40, v252
	v_xad_u32 v103, v252, s0, v40
	v_xad_u32 v104, v252, s1, v40
	v_xad_u32 v105, v252, s4, v40
	ds_read_b128 v[64:67], v72
	ds_read_b128 v[68:71], v72 offset:16
	s_mov_b32 s5, 4
	s_waitcnt lgkmcnt(0)
.Lffl_ia_1:
	ds_read_b128 v[230:233], v72 offset:16384
	ds_read_b128 v[234:237], v72 offset:16400
	s_waitcnt lgkmcnt(6)
	v_add_f32_e32 v30, v64, v66
	v_sub_f32_e32 v32, v64, v66
	v_add_f32_e32 v47, v68, v70
	v_sub_f32_e32 v253, v68, v70
	v_add_f32_e32 v31, v65, v67
	v_sub_f32_e32 v33, v65, v67
	v_add_f32_e32 v250, v69, v71
	v_sub_f32_e32 v254, v69, v71
	v_add_f32_e32 v64, v30, v47
	v_add_f32_e32 v65, v31, v250
	v_sub_f32_e32 v66, v32, v254
	v_add_f32_e32 v67, v33, v253
	v_sub_f32_e32 v68, v30, v47
	v_sub_f32_e32 v69, v31, v250
	v_add_f32_e32 v70, v32, v254
	v_sub_f32_e32 v71, v33, v253
	ds_write_b64 v102, v[64:65]
	ds_write_b64 v103, v[66:67]
	ds_write_b64 v104, v[68:69]
	ds_write_b64 v105, v[70:71]
	ds_read_b128 v[64:67], v72 offset:32768
	ds_read_b128 v[68:71], v72 offset:32784
	s_waitcnt lgkmcnt(6)
	v_add_f32_e32 v30, v230, v232
	v_sub_f32_e32 v32, v230, v232
	v_add_f32_e32 v47, v234, v236
	v_sub_f32_e32 v253, v234, v236
	v_add_f32_e32 v31, v231, v233
	v_sub_f32_e32 v33, v231, v233
	v_add_f32_e32 v250, v235, v237
	v_sub_f32_e32 v254, v235, v237
	v_add_f32_e32 v230, v30, v47
	v_add_f32_e32 v231, v31, v250
	v_sub_f32_e32 v232, v32, v254
	v_add_f32_e32 v233, v33, v253
	v_sub_f32_e32 v234, v30, v47
	v_sub_f32_e32 v235, v31, v250
	v_add_f32_e32 v236, v32, v254
	v_sub_f32_e32 v237, v33, v253
	ds_write_b64 v102, v[230:231] offset:16384
	ds_write_b64 v103, v[232:233] offset:16384
	ds_write_b64 v104, v[234:235] offset:16384
	ds_write_b64 v105, v[236:237] offset:16384
	v_add_u32_e32 v72, 0x8000, v72
	v_add_u32_e32 v102, 0x8000, v102
	v_add_u32_e32 v103, 0x8000, v103
	v_add_u32_e32 v104, 0x8000, v104
	v_add_u32_e32 v105, 0x8000, v105
	s_add_i32 s5, s5, -1
	s_cmp_lg_u32 s5, 0
	s_cbranch_scc1 .Lffl_ia_1
	s_branch .LBB0_722

; DI float cos2pi(float x) { return __builtin_amdgcn_cosf(x); }
; DI float sin2pi(float x) { return __builtin_amdgcn_sinf(x); }
; template <bool INV>
; DI void fft_lds(float2* buf_, int L, int logL, int gtid, int NTG) {
;     ...
;     for (int f = 0; f < nf; ++f, S <<= 2) {
;       const float i4 = 0.25f / (float)S;
; #pragma unroll 8
;       for (int t = gtid; t < (L >> 2); t += NTG) {
;         const int k = t & (S - 1), base = ((t - k) << 2) | k;
;         const v2f p0 = buf[base], p1 = buf[base + S], p2 = buf[base + 2 * S], p3 = buf[base + 3 * S];
;         const float fr = (float)k * i4;
;         const v2f w1 = v2f{cos2pi(fr), sin2pi(fr)};
;         const v2f w2 = vcmul(w1, w1);
;         const v2f b1 = vcmul(p1, w2), b3 = vcmul(p3, w2);
;         const v2f q0 = p0 + b1, q1 = p0 - b1, q2 = p2 + b3, q3 = p2 - b3;
;         const v2f c2 = vcmul(q2, w1);
;         const v2f t3 = vcmul(q3, w1); const v2f c3 = v2f{-t3.y, t3.x};
;         buf[base] = q0 + c2;
;         buf[base + 2 * S] = q0 - c2;
;         buf[base + S] = q1 + c3;
;         buf[base + 3 * S] = q1 - c3;
;       }
;       __syncthreads();
.Lffl_ia_4:
	ds_read_b64 v[230:231], v72 offset:16384
	ds_read_b64 v[232:233], v73 offset:16384
	ds_read_b64 v[234:235], v74 offset:16384
	ds_read_b64 v[236:237], v75 offset:16384
	s_waitcnt lgkmcnt(8)
	v_mul_f32_e32 v251, v67, v109
	v_mul_f32_e32 v252, v67, v108
	v_fma_f32 v110, v66, v108, -v251
	v_fma_f32 v111, v66, v109, v252
	v_mul_f32_e32 v251, v71, v109
	v_mul_f32_e32 v252, v71, v108
	v_fma_f32 v112, v70, v108, -v251
	v_fma_f32 v113, v70, v109, v252
	v_add_f32_e32 v30, v64, v110
	v_sub_f32_e32 v32, v64, v110
	v_add_f32_e32 v47, v68, v112
	v_sub_f32_e32 v253, v68, v112
	v_add_f32_e32 v31, v65, v111
	v_sub_f32_e32 v33, v65, v111
	v_add_f32_e32 v250, v69, v113
	v_sub_f32_e32 v254, v69, v113
	v_mul_f32_e32 v251, v250, v107
	v_mul_f32_e32 v252, v250, v106
	v_fma_f32 v110, v47, v106, -v251
	v_fma_f32 v111, v47, v107, v252
	v_mul_f32_e32 v251, v254, v107
	v_mul_f32_e32 v252, v254, v106
	v_fma_f32 v112, v253, v106, -v251
	v_fma_f32 v113, v253, v107, v252
	v_add_f32_e32 v64, v30, v110
	v_add_f32_e32 v65, v31, v111
	v_sub_f32_e32 v66, v32, v113
	v_add_f32_e32 v67, v33, v112
	v_sub_f32_e32 v68, v30, v110
	v_sub_f32_e32 v69, v31, v111
	v_add_f32_e32 v70, v32, v113
	v_sub_f32_e32 v71, v33, v112
	ds_write_b64 v72, v[64:65]
	ds_write_b64 v73, v[66:67]
	ds_write_b64 v74, v[68:69]
	ds_write_b64 v75, v[70:71]
	ds_read_b64 v[64:65], v72 offset:32768
	ds_read_b64 v[66:67], v73 offset:32768
	ds_read_b64 v[68:69], v74 offset:32768
	ds_read_b64 v[70:71], v75 offset:32768
	s_waitcnt lgkmcnt(8)
	v_mul_f32_e32 v251, v233, v109
	v_mul_f32_e32 v252, v233, v108
	v_fma_f32 v110, v232, v108, -v251
	v_fma_f32 v111, v232, v109, v252
	v_mul_f32_e32 v251, v237, v109
	v_mul_f32_e32 v252, v237, v108
	v_fma_f32 v112, v236, v108, -v251
	v_fma_f32 v113, v236, v109, v252
	v_add_f32_e32 v30, v230, v110
	v_sub_f32_e32 v32, v230, v110
	v_add_f32_e32 v47, v234, v112
	v_sub_f32_e32 v253, v234, v112
	v_add_f32_e32 v31, v231, v111
	v_sub_f32_e32 v33, v231, v111
	v_add_f32_e32 v250, v235, v113
	v_sub_f32_e32 v254, v235, v113
	v_mul_f32_e32 v251, v250, v107
	v_mul_f32_e32 v252, v250, v106
	v_fma_f32 v110, v47, v106, -v251
	v_fma_f32 v111, v47, v107, v252
	v_mul_f32_e32 v251, v254, v107
	v_mul_f32_e32 v252, v254, v106
	v_fma_f32 v112, v253, v106, -v251
	v_fma_f32 v113, v253, v107, v252
	v_add_f32_e32 v230, v30, v110
	v_add_f32_e32 v231, v31, v111
	v_sub_f32_e32 v232, v32, v113
	v_add_f32_e32 v233, v33, v112
	v_sub_f32_e32 v234, v30, v110
	v_sub_f32_e32 v235, v31, v111
	v_add_f32_e32 v236, v32, v113
	v_sub_f32_e32 v237, v33, v112
	ds_write_b64 v72, v[230:231] offset:16384
	ds_write_b64 v73, v[232:233] offset:16384
	ds_write_b64 v74, v[234:235] offset:16384
	ds_write_b64 v75, v[236:237] offset:16384
	v_add_u32_e32 v72, 0x8000, v72
	v_add_u32_e32 v73, 0x8000, v73
	v_add_u32_e32 v74, 0x8000, v74
	v_add_u32_e32 v75, 0x8000, v75
	s_add_i32 s5, s5, -1
	s_cmp_lg_u32 s5, 0
	s_cbranch_scc1 .Lffl_ia_4
	s_branch .LBB0_722
.Lffs_ia_16:
	s_movk_i32 s0, 0x80
	s_movk_i32 s1, 0x128
	s_movk_i32 s4, 0x1a8
	v_and_b32_e32 v250, 15, v38
	v_sub_u32_e32 v251, v38, v250
	v_lshl_or_b32 v251, v251, 2, v250
	v_cvt_f32_u32_e32 v250, v250
	v_mul_f32_e32 v250, 0x3c800000, v250
	v_cos_f32_e32 v106, v250
	v_sin_f32_e32 v107, v250
	v_lshl_add_u32 v102, v251, 3, v40
	v_add_u32_e32 v103, 0x80, v102
	v_add_u32_e32 v104, 0x100, v102
	v_add_u32_e32 v105, 0x180, v102
	v_bfe_u32 v252, v251, 5, 2
	v_bfe_u32 v253, v251, 6, 1
	v_lshl_or_b32 v252, v252, 2, v252
	v_lshl_or_b32 v252, v253, 4, v252
	v_xor_b32_e32 v252, v252, v251
	v_lshlrev_b32_e32 v252, 3, v252
	v_add_u32_e32 v72, v40, v252
	v_xad_u32 v73, v252, s0, v40
	v_xad_u32 v74, v252, s1, v40
	v_xad_u32 v75, v252, s4, v40
	v_mul_f32_e32 v108, v107, v107
	v_mul_f32_e32 v109, v107, v106
	v_fma_f32 v108, v106, v106, -v108
	v_fma_f32 v109, v106, v107, v109
	ds_read_b64 v[64:65], v72
	ds_read_b64 v[66:67], v73
	ds_read_b64 v[68:69], v74
	ds_read_b64 v[70:71], v75
	s_mov_b32 s5, 4
	s_waitcnt lgkmcnt(0)
.Lffl_ia_16:
	ds_read_b64 v[230:231], v72 offset:16384
	ds_read_b64 v[232:233], v73 offset:16384
	ds_read_b64 v[234:235], v74 offset:16384
	ds_read_b64 v[236:237], v75 offset:16384
	s_waitcnt lgkmcnt(8)
	v_mul_f32_e32 v251, v67, v109
	v_mul_f32_e32 v252, v67, v108
	v_fma_f32 v110, v66, v108, -v251
	v_fma_f32 v111, v66, v109, v252
	v_mul_f32_e32 v251, v71, v109
	v_mul_f32_e32 v252, v71, v108
	v_fma_f32 v112, v70, v108, -v251
	v_fma_f32 v113, v70, v109, v252
	v_add_f32_e32 v30, v64, v110
	v_sub_f32_e32 v32, v64, v110
	v_add_f32_e32 v47, v68, v112
	v_sub_f32_e32 v253, v68, v112
	v_add_f32_e32 v31, v65, v111
	v_sub_f32_e32 v33, v65, v111
	v_add_f32_e32 v250, v69, v113
	v_sub_f32_e32 v254, v69, v113
	v_mul_f32_e32 v251, v250, v107
	v_mul_f32_e32 v252, v250, v106
	v_fma_f32 v110, v47, v106, -v251
	v_fma_f32 v111, v47, v107, v252
	v_mul_f32_e32 v251, v254, v107
	v_mul_f32_e32 v252, v254, v106
	v_fma_f32 v112, v253, v106, -v251
	v_fma_f32 v113, v253, v107, v252
	v_add_f32_e32 v64, v30, v110
	v_add_f32_e32 v65, v31, v111
	v_sub_f32_e32 v66, v32, v113
	v_add_f32_e32 v67, v33, v112
	v_sub_f32_e32 v68, v30, v110
	v_sub_f32_e32 v69, v31, v111
	v_add_f32_e32 v70, v32, v113
	v_sub_f32_e32 v71, v33, v112
	ds_write_b64 v102, v[64:65]
	ds_write_b64 v103, v[66:67]
	ds_write_b64 v104, v[68:69]
	ds_write_b64 v105, v[70:71]
	ds_read_b64 v[64:65], v72 offset:32768
	ds_read_b64 v[66:67], v73 offset:32768
	ds_read_b64 v[68:69], v74 offset:32768
	ds_read_b64 v[70:71], v75 offset:32768
	s_waitcnt lgkmcnt(8)
	v_mul_f32_e32 v251, v233, v109
	v_mul_f32_e32 v252, v233, v108
	v_fma_f32 v110, v232, v108, -v251
	v_fma_f32 v111, v232, v109, v252
	v_mul_f32_e32 v251, v237, v109
	v_mul_f32_e32 v252, v237, v108
	v_fma_f32 v112, v236, v108, -v251
	v_fma_f32 v113, v236, v109, v252
	v_add_f32_e32 v30, v230, v110
	v_sub_f32_e32 v32, v230, v110
	v_add_f32_e32 v47, v234, v112
	v_sub_f32_e32 v253, v234, v112
	v_add_f32_e32 v31, v231, v111
	v_sub_f32_e32 v33, v231, v111
	v_add_f32_e32 v250, v235, v113
	v_sub_f32_e32 v254, v235, v113
	v_mul_f32_e32 v251, v250, v107
	v_mul_f32_e32 v252, v250, v106
	v_fma_f32 v110, v47, v106, -v251
	v_fma_f32 v111, v47, v107, v252
	v_mul_f32_e32 v251, v254, v107
	v_mul_f32_e32 v252, v254, v106
	v_fma_f32 v112, v253, v106, -v251
	v_fma_f32 v113, v253, v107, v252
	v_add_f32_e32 v230, v30, v110
	v_add_f32_e32 v231, v31, v111
	v_sub_f32_e32 v232, v32, v113
	v_add_f32_e32 v233, v33, v112
	v_sub_f32_e32 v234, v30, v110
	v_sub_f32_e32 v235, v31, v111
	v_add_f32_e32 v236, v32, v113
	v_sub_f32_e32 v237, v33, v112
	ds_write_b64 v102, v[230:231] offset:16384
	ds_write_b64 v103, v[232:233] offset:16384
	ds_write_b64 v104, v[234:235] offset:16384
	ds_write_b64 v105, v[236:237] offset:16384
	v_add_u32_e32 v72, 0x8000, v72
	v_add_u32_e32 v73, 0x8000, v73
	v_add_u32_e32 v74, 0x8000, v74
	v_add_u32_e32 v75, 0x8000, v75
	v_add_u32_e32 v102, 0x8000, v102
	v_add_u32_e32 v103, 0x8000, v103
	v_add_u32_e32 v104, 0x8000, v104
	v_add_u32_e32 v105, 0x8000, v105
	s_add_i32 s5, s5, -1
	s_cmp_lg_u32 s5, 0
	s_cbranch_scc1 .Lffl_ia_16
	s_branch .LBB0_722

; DI float cos2pi(float x) { return __builtin_amdgcn_cosf(x); }
; DI float sin2pi(float x) { return __builtin_amdgcn_sinf(x); }
; template <bool INV>
; DI void fft_lds(float2* buf_, int L, int logL, int gtid, int NTG) {
;     ...
;     for (int f = 0; f < nf; ++f, S <<= 2) {
;       const float i4 = 0.25f / (float)S;
; #pragma unroll 8
;       for (int t = gtid; t < (L >> 2); t += NTG) {
;         const int k = t & (S - 1), base = ((t - k) << 2) | k;
;         const v2f p0 = buf[base], p1 = buf[base + S], p2 = buf[base + 2 * S], p3 = buf[base + 3 * S];
;         const float fr = (float)k * i4;
;         const v2f w1 = v2f{cos2pi(fr), sin2pi(fr)};
;         const v2f w2 = vcmul(w1, w1);
;         const v2f b1 = vcmul(p1, w2), b3 = vcmul(p3, w2);
;         const v2f q0 = p0 + b1, q1 = p0 - b1, q2 = p2 + b3, q3 = p2 - b3;
;         const v2f c2 = vcmul(q2, w1);
;         const v2f t3 = vcmul(q3, w1); const v2f c3 = v2f{-t3.y, t3.x};
;         buf[base] = q0 + c2;
;         buf[base + 2 * S] = q0 - c2;
;         buf[base + S] = q1 + c3;
;         buf[base + 3 * S] = q1 - c3;
;       }
;       __syncthreads();
.Lffl_ia_256:
	ds_read_b64 v[230:231], v72 offset:16384
	ds_read_b64 v[232:233], v73 offset:16384
	ds_read_b64 v[234:235], v74 offset:16384
	ds_read_b64 v[236:237], v75 offset:16384
	s_waitcnt lgkmcnt(8)
	v_mul_f32_e32 v251, v67, v109
	v_mul_f32_e32 v252, v67, v108
	v_fma_f32 v110, v66, v108, -v251
	v_fma_f32 v111, v66, v109, v252
	v_mul_f32_e32 v251, v71, v109
	v_mul_f32_e32 v252, v71, v108
	v_fma_f32 v112, v70, v108, -v251
	v_fma_f32 v113, v70, v109, v252
	v_add_f32_e32 v30, v64, v110
	v_sub_f32_e32 v32, v64, v110
	v_add_f32_e32 v47, v68, v112
	v_sub_f32_e32 v253, v68, v112
	v_add_f32_e32 v31, v65, v111
	v_sub_f32_e32 v33, v65, v111
	v_add_f32_e32 v250, v69, v113
	v_sub_f32_e32 v254, v69, v113
	v_mul_f32_e32 v251, v250, v107
	v_mul_f32_e32 v252, v250, v106
	v_fma_f32 v110, v47, v106, -v251
	v_fma_f32 v111, v47, v107, v252
	v_mul_f32_e32 v251, v254, v107
	v_mul_f32_e32 v252, v254, v106
	v_fma_f32 v112, v253, v106, -v251
	v_fma_f32 v113, v253, v107, v252
	v_add_f32_e32 v64, v30, v110
	v_add_f32_e32 v65, v31, v111
	v_sub_f32_e32 v66, v32, v113
	v_add_f32_e32 v67, v33, v112
	v_sub_f32_e32 v68, v30, v110
	v_sub_f32_e32 v69, v31, v111
	v_add_f32_e32 v70, v32, v113
	v_sub_f32_e32 v71, v33, v112
	ds_write_b64 v72, v[64:65]
	ds_write_b64 v73, v[66:67]
	ds_write_b64 v74, v[68:69]
	ds_write_b64 v75, v[70:71]
	ds_read_b64 v[64:65], v72 offset:32768
	ds_read_b64 v[66:67], v73 offset:32768
	ds_read_b64 v[68:69], v74 offset:32768
	ds_read_b64 v[70:71], v75 offset:32768
	s_waitcnt lgkmcnt(8)
	v_mul_f32_e32 v251, v233, v109
	v_mul_f32_e32 v252, v233, v108
	v_fma_f32 v110, v232, v108, -v251
	v_fma_f32 v111, v232, v109, v252
	v_mul_f32_e32 v251, v237, v109
	v_mul_f32_e32 v252, v237, v108
	v_fma_f32 v112, v236, v108, -v251
	v_fma_f32 v113, v236, v109, v252
	v_add_f32_e32 v30, v230, v110
	v_sub_f32_e32 v32, v230, v110
	v_add_f32_e32 v47, v234, v112
	v_sub_f32_e32 v253, v234, v112
	v_add_f32_e32 v31, v231, v111
	v_sub_f32_e32 v33, v231, v111
	v_add_f32_e32 v250, v235, v113
	v_sub_f32_e32 v254, v235, v113
	v_mul_f32_e32 v251, v250, v107
	v_mul_f32_e32 v252, v250, v106
	v_fma_f32 v110, v47, v106, -v251
	v_fma_f32 v111, v47, v107, v252
	v_mul_f32_e32 v251, v254, v107
	v_mul_f32_e32 v252, v254, v106
	v_fma_f32 v112, v253, v106, -v251
	v_fma_f32 v113, v253, v107, v252
	v_add_f32_e32 v230, v30, v110
	v_add_f32_e32 v231, v31, v111
	v_sub_f32_e32 v232, v32, v113
	v_add_f32_e32 v233, v33, v112
	v_sub_f32_e32 v234, v30, v110
	v_sub_f32_e32 v235, v31, v111
	v_add_f32_e32 v236, v32, v113
	v_sub_f32_e32 v237, v33, v112
	ds_write_b64 v72, v[230:231] offset:16384
	ds_write_b64 v73, v[232:233] offset:16384
	ds_write_b64 v74, v[234:235] offset:16384
	ds_write_b64 v75, v[236:237] offset:16384
	v_add_u32_e32 v72, 0x8000, v72
	v_add_u32_e32 v73, 0x8000, v73
	v_add_u32_e32 v74, 0x8000, v74
	v_add_u32_e32 v75, 0x8000, v75
	s_add_i32 s5, s5, -1
	s_cmp_lg_u32 s5, 0
	s_cbranch_scc1 .Lffl_ia_256
	s_branch .LBB0_722
	s_branch .Lffs_i_skip

; DI float cos2pi(float x) { return __builtin_amdgcn_cosf(x); }
; DI float sin2pi(float x) { return __builtin_amdgcn_sinf(x); }
; template <bool INV>
; DI void fft_lds(float2* buf_, int L, int logL, int gtid, int NTG) {
;     ...
;     for (int f = 0; f < nf; ++f, S <<= 2) {
;       const float i4 = 0.25f / (float)S;
; #pragma unroll 8
;       for (int t = gtid; t < (L >> 2); t += NTG) {
;         const int k = t & (S - 1), base = ((t - k) << 2) | k;
;         const v2f p0 = buf[base], p1 = buf[base + S], p2 = buf[base + 2 * S], p3 = buf[base + 3 * S];
;         const float fr = (float)k * i4;
;         const v2f w1 = v2f{cos2pi(fr), sin2pi(fr)};
;         const v2f w2 = vcmul(w1, w1);
;         const v2f b1 = vcmul(p1, w2), b3 = vcmul(p3, w2);
;         const v2f q0 = p0 + b1, q1 = p0 - b1, q2 = p2 + b3, q3 = p2 - b3;
;         const v2f c2 = vcmul(q2, w1);
;         const v2f t3 = vcmul(q3, w1); const v2f c3 = v2f{-t3.y, t3.x};
;         buf[base] = q0 + c2;
;         buf[base + 2 * S] = q0 - c2;
;         buf[base + S] = q1 + c3;
;         buf[base + 3 * S] = q1 - c3;
;       }
;       __syncthreads();
.Lffs_i_n64:
	s_cmp_gt_u32 s7, 64
	s_cbranch_scc1 .Lffs_ib_skip
	s_cmp_eq_u32 s7, 64
	s_cbranch_scc1 .Lffs_ib_64
	s_cmp_eq_u32 s7, 16
	s_cbranch_scc1 .Lffs_ib_16
	s_cmp_eq_u32 s7, 4
	s_cbranch_scc1 .Lffs_ib_4
	s_movk_i32 s0, 0x8
	s_movk_i32 s1, 0x10
	s_movk_i32 s4, 0x18
	v_lshlrev_b32_e32 v251, 2, v38
	v_lshl_add_u32 v72, v251, 3, v40
	v_bfe_u32 v252, v251, 5, 2
	v_bfe_u32 v253, v251, 6, 1
	v_lshl_or_b32 v252, v252, 2, v252
	v_lshl_or_b32 v252, v253, 4, v252
	v_xor_b32_e32 v252, v252, v251
	v_lshlrev_b32_e32 v252, 3, v252
	v_add_u32_e32 v102, v40, v252
	v_xad_u32 v103, v252, s0, v40
	v_xad_u32 v104, v252, s1, v40
	v_xad_u32 v105, v252, s4, v40
	ds_read_b128 v[64:67], v72
	ds_read_b128 v[68:71], v72 offset:16
	s_mov_b32 s5, 4
	s_waitcnt lgkmcnt(0)
.Lffl_ib_1:
	ds_read_b128 v[230:233], v72 offset:2048
	ds_read_b128 v[234:237], v72 offset:2064
	s_waitcnt lgkmcnt(6)
	v_add_f32_e32 v30, v64, v66
	v_sub_f32_e32 v32, v64, v66
	v_add_f32_e32 v47, v68, v70
	v_sub_f32_e32 v253, v68, v70
	v_add_f32_e32 v31, v65, v67
	v_sub_f32_e32 v33, v65, v67
	v_add_f32_e32 v250, v69, v71
	v_sub_f32_e32 v254, v69, v71
	v_add_f32_e32 v64, v30, v47
	v_add_f32_e32 v65, v31, v250
	v_sub_f32_e32 v66, v32, v254
	v_add_f32_e32 v67, v33, v253
	v_sub_f32_e32 v68, v30, v47
	v_sub_f32_e32 v69, v31, v250
	v_add_f32_e32 v70, v32, v254
	v_sub_f32_e32 v71, v33, v253
	ds_write_b64 v102, v[64:65]
	ds_write_b64 v103, v[66:67]
	ds_write_b64 v104, v[68:69]
	ds_write_b64 v105, v[70:71]
	ds_read_b128 v[64:67], v72 offset:4096
	ds_read_b128 v[68:71], v72 offset:4112
	s_waitcnt lgkmcnt(6)
	v_add_f32_e32 v30, v230, v232
	v_sub_f32_e32 v32, v230, v232
	v_add_f32_e32 v47, v234, v236
	v_sub_f32_e32 v253, v234, v236
	v_add_f32_e32 v31, v231, v233
	v_sub_f32_e32 v33, v231, v233
	v_add_f32_e32 v250, v235, v237
	v_sub_f32_e32 v254, v235, v237
	v_add_f32_e32 v230, v30, v47
	v_add_f32_e32 v231, v31, v250
	v_sub_f32_e32 v232, v32, v254
	v_add_f32_e32 v233, v33, v253
	v_sub_f32_e32 v234, v30, v47
	v_sub_f32_e32 v235, v31, v250
	v_add_f32_e32 v236, v32, v254
	v_sub_f32_e32 v237, v33, v253
	ds_write_b64 v102, v[230:231] offset:2048
	ds_write_b64 v103, v[232:233] offset:2048
	ds_write_b64 v104, v[234:235] offset:2048
	ds_write_b64 v105, v[236:237] offset:2048
	v_add_u32_e32 v72, 0x1000, v72
	v_add_u32_e32 v102, 0x1000, v102
	v_add_u32_e32 v103, 0x1000, v103
	v_add_u32_e32 v104, 0x1000, v104
	v_add_u32_e32 v105, 0x1000, v105
	s_add_i32 s5, s5, -1
	s_cmp_lg_u32 s5, 0
	s_cbranch_scc1 .Lffl_ib_1
	s_branch .LBB0_722

; DI float cos2pi(float x) { return __builtin_amdgcn_cosf(x); }
; DI float sin2pi(float x) { return __builtin_amdgcn_sinf(x); }
; template <bool INV>
; DI void fft_lds(float2* buf_, int L, int logL, int gtid, int NTG) {
;     ...
;     for (int f = 0; f < nf; ++f, S <<= 2) {
;       const float i4 = 0.25f / (float)S;
; #pragma unroll 8
;       for (int t = gtid; t < (L >> 2); t += NTG) {
;         const int k = t & (S - 1), base = ((t - k) << 2) | k;
;         const v2f p0 = buf[base], p1 = buf[base + S], p2 = buf[base + 2 * S], p3 = buf[base + 3 * S];
;         const float fr = (float)k * i4;
;         const v2f w1 = v2f{cos2pi(fr), sin2pi(fr)};
;         const v2f w2 = vcmul(w1, w1);
;         const v2f b1 = vcmul(p1, w2), b3 = vcmul(p3, w2);
;         const v2f q0 = p0 + b1, q1 = p0 - b1, q2 = p2 + b3, q3 = p2 - b3;
;         const v2f c2 = vcmul(q2, w1);
;         const v2f t3 = vcmul(q3, w1); const v2f c3 = v2f{-t3.y, t3.x};
;         buf[base] = q0 + c2;
;         buf[base + 2 * S] = q0 - c2;
;         buf[base + S] = q1 + c3;
;         buf[base + 3 * S] = q1 - c3;
;       }
;       __syncthreads();
.Lffl_ib_4:
	ds_read_b64 v[230:231], v72 offset:2048
	ds_read_b64 v[232:233], v73 offset:2048
	ds_read_b64 v[234:235], v74 offset:2048
	ds_read_b64 v[236:237], v75 offset:2048
	s_waitcnt lgkmcnt(8)
	v_mul_f32_e32 v251, v67, v109
	v_mul_f32_e32 v252, v67, v108
	v_fma_f32 v110, v66, v108, -v251
	v_fma_f32 v111, v66, v109, v252
	v_mul_f32_e32 v251, v71, v109
	v_mul_f32_e32 v252, v71, v108
	v_fma_f32 v112, v70, v108, -v251
	v_fma_f32 v113, v70, v109, v252
	v_add_f32_e32 v30, v64, v110
	v_sub_f32_e32 v32, v64, v110
	v_add_f32_e32 v47, v68, v112
	v_sub_f32_e32 v253, v68, v112
	v_add_f32_e32 v31, v65, v111
	v_sub_f32_e32 v33, v65, v111
	v_add_f32_e32 v250, v69, v113
	v_sub_f32_e32 v254, v69, v113
	v_mul_f32_e32 v251, v250, v107
	v_mul_f32_e32 v252, v250, v106
	v_fma_f32 v110, v47, v106, -v251
	v_fma_f32 v111, v47, v107, v252
	v_mul_f32_e32 v251, v254, v107
	v_mul_f32_e32 v252, v254, v106
	v_fma_f32 v112, v253, v106, -v251
	v_fma_f32 v113, v253, v107, v252
	v_add_f32_e32 v64, v30, v110
	v_add_f32_e32 v65, v31, v111
	v_sub_f32_e32 v66, v32, v113
	v_add_f32_e32 v67, v33, v112
	v_sub_f32_e32 v68, v30, v110
	v_sub_f32_e32 v69, v31, v111
	v_add_f32_e32 v70, v32, v113
	v_sub_f32_e32 v71, v33, v112
	ds_write_b64 v72, v[64:65]
	ds_write_b64 v73, v[66:67]
	ds_write_b64 v74, v[68:69]
	ds_write_b64 v75, v[70:71]
	ds_read_b64 v[64:65], v72 offset:4096
	ds_read_b64 v[66:67], v73 offset:4096
	ds_read_b64 v[68:69], v74 offset:4096
	ds_read_b64 v[70:71], v75 offset:4096
	s_waitcnt lgkmcnt(8)
	v_mul_f32_e32 v251, v233, v109
	v_mul_f32_e32 v252, v233, v108
	v_fma_f32 v110, v232, v108, -v251
	v_fma_f32 v111, v232, v109, v252
	v_mul_f32_e32 v251, v237, v109
	v_mul_f32_e32 v252, v237, v108
	v_fma_f32 v112, v236, v108, -v251
	v_fma_f32 v113, v236, v109, v252
	v_add_f32_e32 v30, v230, v110
	v_sub_f32_e32 v32, v230, v110
	v_add_f32_e32 v47, v234, v112
	v_sub_f32_e32 v253, v234, v112
	v_add_f32_e32 v31, v231, v111
	v_sub_f32_e32 v33, v231, v111
	v_add_f32_e32 v250, v235, v113
	v_sub_f32_e32 v254, v235, v113
	v_mul_f32_e32 v251, v250, v107
	v_mul_f32_e32 v252, v250, v106
	v_fma_f32 v110, v47, v106, -v251
	v_fma_f32 v111, v47, v107, v252
	v_mul_f32_e32 v251, v254, v107
	v_mul_f32_e32 v252, v254, v106
	v_fma_f32 v112, v253, v106, -v251
	v_fma_f32 v113, v253, v107, v252
	v_add_f32_e32 v230, v30, v110
	v_add_f32_e32 v231, v31, v111
	v_sub_f32_e32 v232, v32, v113
	v_add_f32_e32 v233, v33, v112
	v_sub_f32_e32 v234, v30, v110
	v_sub_f32_e32 v235, v31, v111
	v_add_f32_e32 v236, v32, v113
	v_sub_f32_e32 v237, v33, v112
	ds_write_b64 v72, v[230:231] offset:2048
	ds_write_b64 v73, v[232:233] offset:2048
	ds_write_b64 v74, v[234:235] offset:2048
	ds_write_b64 v75, v[236:237] offset:2048
	v_add_u32_e32 v72, 0x1000, v72
	v_add_u32_e32 v73, 0x1000, v73
	v_add_u32_e32 v74, 0x1000, v74
	v_add_u32_e32 v75, 0x1000, v75
	s_add_i32 s5, s5, -1
	s_cmp_lg_u32 s5, 0
	s_cbranch_scc1 .Lffl_ib_4
	s_branch .LBB0_722

; DI float cos2pi(float x) { return __builtin_amdgcn_cosf(x); }
; DI float sin2pi(float x) { return __builtin_amdgcn_sinf(x); }
; template <bool INV>
; DI void fft_lds(float2* buf_, int L, int logL, int gtid, int NTG) {
;     ...
;     for (int f = 0; f < nf; ++f, S <<= 2) {
;       const float i4 = 0.25f / (float)S;
; #pragma unroll 8
;       for (int t = gtid; t < (L >> 2); t += NTG) {
;         const int k = t & (S - 1), base = ((t - k) << 2) | k;
;         const v2f p0 = buf[base], p1 = buf[base + S], p2 = buf[base + 2 * S], p3 = buf[base + 3 * S];
;         const float fr = (float)k * i4;
;         const v2f w1 = v2f{cos2pi(fr), sin2pi(fr)};
;         const v2f w2 = vcmul(w1, w1);
;         const v2f b1 = vcmul(p1, w2), b3 = vcmul(p3, w2);
;         const v2f q0 = p0 + b1, q1 = p0 - b1, q2 = p2 + b3, q3 = p2 - b3;
;         const v2f c2 = vcmul(q2, w1);
;         const v2f t3 = vcmul(q3, w1); const v2f c3 = v2f{-t3.y, t3.x};
;         buf[base] = q0 + c2;
;         buf[base + 2 * S] = q0 - c2;
;         buf[base + S] = q1 + c3;
;         buf[base + 3 * S] = q1 - c3;
;       }
;       __syncthreads();
.Lffl_ib_16:
	ds_read_b64 v[230:231], v72 offset:2048
	ds_read_b64 v[232:233], v73 offset:2048
	ds_read_b64 v[234:235], v74 offset:2048
	ds_read_b64 v[236:237], v75 offset:2048
	s_waitcnt lgkmcnt(8)
	v_mul_f32_e32 v251, v67, v109
	v_mul_f32_e32 v252, v67, v108
	v_fma_f32 v110, v66, v108, -v251
	v_fma_f32 v111, v66, v109, v252
	v_mul_f32_e32 v251, v71, v109
	v_mul_f32_e32 v252, v71, v108
	v_fma_f32 v112, v70, v108, -v251
	v_fma_f32 v113, v70, v109, v252
	v_add_f32_e32 v30, v64, v110
	v_sub_f32_e32 v32, v64, v110
	v_add_f32_e32 v47, v68, v112
	v_sub_f32_e32 v253, v68, v112
	v_add_f32_e32 v31, v65, v111
	v_sub_f32_e32 v33, v65, v111
	v_add_f32_e32 v250, v69, v113
	v_sub_f32_e32 v254, v69, v113
	v_mul_f32_e32 v251, v250, v107
	v_mul_f32_e32 v252, v250, v106
	v_fma_f32 v110, v47, v106, -v251
	v_fma_f32 v111, v47, v107, v252
	v_mul_f32_e32 v251, v254, v107
	v_mul_f32_e32 v252, v254, v106
	v_fma_f32 v112, v253, v106, -v251
	v_fma_f32 v113, v253, v107, v252
	v_add_f32_e32 v64, v30, v110
	v_add_f32_e32 v65, v31, v111
	v_sub_f32_e32 v66, v32, v113
	v_add_f32_e32 v67, v33, v112
	v_sub_f32_e32 v68, v30, v110
	v_sub_f32_e32 v69, v31, v111
	v_add_f32_e32 v70, v32, v113
	v_sub_f32_e32 v71, v33, v112
	ds_write_b64 v102, v[64:65]
	ds_write_b64 v103, v[66:67]
	ds_write_b64 v104, v[68:69]
	ds_write_b64 v105, v[70:71]
	ds_read_b64 v[64:65], v72 offset:4096
	ds_read_b64 v[66:67], v73 offset:4096
	ds_read_b64 v[68:69], v74 offset:4096
	ds_read_b64 v[70:71], v75 offset:4096
	s_waitcnt lgkmcnt(8)
	v_mul_f32_e32 v251, v233, v109
	v_mul_f32_e32 v252, v233, v108
	v_fma_f32 v110, v232, v108, -v251
	v_fma_f32 v111, v232, v109, v252
	v_mul_f32_e32 v251, v237, v109
	v_mul_f32_e32 v252, v237, v108
	v_fma_f32 v112, v236, v108, -v251
	v_fma_f32 v113, v236, v109, v252
	v_add_f32_e32 v30, v230, v110
	v_sub_f32_e32 v32, v230, v110
	v_add_f32_e32 v47, v234, v112
	v_sub_f32_e32 v253, v234, v112
	v_add_f32_e32 v31, v231, v111
	v_sub_f32_e32 v33, v231, v111
	v_add_f32_e32 v250, v235, v113
	v_sub_f32_e32 v254, v235, v113
	v_mul_f32_e32 v251, v250, v107
	v_mul_f32_e32 v252, v250, v106
	v_fma_f32 v110, v47, v106, -v251
	v_fma_f32 v111, v47, v107, v252
	v_mul_f32_e32 v251, v254, v107
	v_mul_f32_e32 v252, v254, v106
	v_fma_f32 v112, v253, v106, -v251
	v_fma_f32 v113, v253, v107, v252
	v_add_f32_e32 v230, v30, v110
	v_add_f32_e32 v231, v31, v111
	v_sub_f32_e32 v232, v32, v113
	v_add_f32_e32 v233, v33, v112
	v_sub_f32_e32 v234, v30, v110
	v_sub_f32_e32 v235, v31, v111
	v_add_f32_e32 v236, v32, v113
	v_sub_f32_e32 v237, v33, v112
	ds_write_b64 v102, v[230:231] offset:2048
	ds_write_b64 v103, v[232:233] offset:2048
	ds_write_b64 v104, v[234:235] offset:2048
	ds_write_b64 v105, v[236:237] offset:2048
	v_add_u32_e32 v72, 0x1000, v72
	v_add_u32_e32 v73, 0x1000, v73
	v_add_u32_e32 v74, 0x1000, v74
	v_add_u32_e32 v75, 0x1000, v75
	v_add_u32_e32 v102, 0x1000, v102
	v_add_u32_e32 v103, 0x1000, v103
	v_add_u32_e32 v104, 0x1000, v104
	v_add_u32_e32 v105, 0x1000, v105
	s_add_i32 s5, s5, -1
	s_cmp_lg_u32 s5, 0
	s_cbranch_scc1 .Lffl_ib_16
	s_branch .LBB0_722

; template <bool INV>
; DI void fft_lds(float2* buf_, int L, int logL, int gtid, int NTG) {
;     ...
;     for (int f = 0; f < nf; ++f, S <<= 2) {
;       const float i4 = 0.25f / (float)S;
; #pragma unroll 8
;       for (int t = gtid; t < (L >> 2); t += NTG) {
;         const int k = t & (S - 1), base = ((t - k) << 2) | k;
;         const v2f p0 = buf[base], p1 = buf[base + S], p2 = buf[base + 2 * S], p3 = buf[base + 3 * S];
.Lffs_ib_skip:
.Lffs_i_skip:
	v_cvt_f32_i32_e32 v30, s7
	s_add_i32 s24, s7, -1
	v_lshl_add_u32 v32, s7, 3, v40
	v_div_scale_f32 v31, s[0:1], v30, v30, s60
	v_rcp_f32_e32 v33, v31
	v_div_scale_f32 v47, vcc, s60, v30, s60
	v_fma_f32 v64, -v31, v33, 1.0
	v_fmac_f32_e32 v33, v64, v33
	v_mul_f32_e32 v64, v47, v33
	v_fma_f32 v65, -v31, v64, v47
	v_fmac_f32_e32 v64, v65, v33
	v_fma_f32 v31, -v31, v64, v47
	v_div_fmas_f32 v31, v31, v33, v64
	v_div_fixup_f32 v33, v31, v30, s60
	v_lshl_add_u32 v47, s7, 4, v40
	v_mov_b32_e32 v64, v38
	s_and_saveexec_b64 s[0:1], s[48:49]
	s_cbranch_execz .LBB0_728
	v_mad_u64_u32 v[30:31], s[4:5], s7, 24, v[40:41]
	s_mov_b64 s[4:5], 0
	v_mov_b32_e32 v31, v90
	v_mov_b32_e32 v65, v101
	v_mov_b32_e32 v64, v38
